# phase 5: first staging loop fully unrolled with all loads issued up front; epilogue gate/gain loads prefetched into spare registers
# speedup vs baseline: 1.0056x; 1.0056x over previous
.LBB0_312:
	v_lshl_add_u64 v[8:9], s[26:27], 0, v[0:1]
	v_add_co_u32_e64 v12, s[0:1], s64, v8
	v_lshl_add_u64 v[6:7], s[26:27], 0, v[2:3]
	s_nop 0
	v_addc_co_u32_e64 v13, s[0:1], 0, v9, s[0:1]
	v_add_co_u32_e64 v14, s[0:1], s65, v6
	v_add_co_u32_e32 v10, vcc, 0x5800000, v6
	s_nop 0
	v_addc_co_u32_e64 v15, s[0:1], 0, v7, s[0:1]
	v_add_co_u32_e64 v18, s[0:1], s70, v6
	v_addc_co_u32_e32 v11, vcc, 0, v7, vcc
	s_nop 0
	v_addc_co_u32_e64 v19, s[0:1], 0, v7, s[0:1]
	v_add_co_u32_e64 v20, s[0:1], s68, v8
	v_add_u32_e32 v5, s6, v4
	s_nop 0
	v_addc_co_u32_e64 v21, s[0:1], 0, v9, s[0:1]
	v_add_co_u32_e64 v22, s[0:1], s69, v8
	s_addk_i32 s6, 0x880
	s_nop 0
	v_addc_co_u32_e64 v23, s[0:1], 0, v9, s[0:1]
	v_add_co_u32_e64 v24, s[0:1], s71, v8
	v_lshl_add_u64 v[0:1], v[0:1], 0, s[8:9]
	s_nop 0
	v_addc_co_u32_e64 v25, s[0:1], 0, v9, s[0:1]
	v_add_co_u32_e64 v26, s[0:1], s72, v8
	v_lshl_add_u64 v[2:3], v[2:3], 0, s[10:11]
	s_nop 0
	v_addc_co_u32_e64 v27, s[0:1], 0, v9, s[0:1]
	v_add_co_u32_e64 v28, s[0:1], s73, v6
	v_add_co_u32_e32 v6, vcc, 0x9800000, v8
	s_nop 0
	v_addc_co_u32_e64 v29, s[0:1], 0, v7, s[0:1]
	v_add_co_u32_e64 v30, s[0:1], s74, v8
	global_load_ushort v16, v[20:21], off
	s_nop 0
	global_load_ushort v20, v[20:21], off offset:1024
	s_nop 0
	global_load_dword v21, v[18:19], off offset:-4096
	global_load_ushort v34, v[22:23], off offset:2048
	s_nop 0
	global_load_ushort v22, v[22:23], off offset:3072
	s_nop 0
	global_load_ushort v23, v[24:25], off
	s_nop 0
	global_load_ushort v24, v[24:25], off offset:1024
	s_nop 0
	global_load_dword v25, v[18:19], off
	s_nop 0
	global_load_dword v18, v[18:19], off offset:2048
	s_nop 0
	global_load_ushort v19, v[26:27], off offset:2048
	s_nop 0
	global_load_ushort v26, v[26:27], off offset:3072
	v_addc_co_u32_e64 v31, s[0:1], 0, v9, s[0:1]
	v_add_co_u32_e64 v32, s[0:1], s75, v8
	v_addc_co_u32_e32 v7, vcc, 0, v9, vcc
	s_nop 0
	v_addc_co_u32_e64 v33, s[0:1], 0, v9, s[0:1]
	global_load_ushort v27, v[30:31], off
	s_nop 0
	global_load_ushort v30, v[30:31], off offset:1024
	s_nop 0
	global_load_dword v31, v[28:29], off
	global_load_ushort v35, v[32:33], off offset:2048
	s_nop 0
	global_load_ushort v32, v[32:33], off offset:3072
	s_nop 0
	global_load_dword v28, v[28:29], off offset:2048
	global_load_dword v8, v[10:11], off
	global_load_ushort v9, v[6:7], off
	s_nop 0
	global_load_ushort v6, v[6:7], off offset:1024
	s_nop 0
	global_load_ushort v7, v[12:13], off offset:2048
	s_nop 0
	global_load_ushort v12, v[12:13], off offset:3072
	s_nop 0
	global_load_dword v13, v[14:15], off offset:2048
	s_nop 0
	global_load_dword v10, v[10:11], off offset:2048
	v_lshl_add_u64 v[44:45], s[26:27], 0, v[0:1]
	v_add_co_u32_e64 v48, s[0:1], s64, v44
	v_lshl_add_u64 v[42:43], s[26:27], 0, v[2:3]
	s_nop 0
	v_addc_co_u32_e64 v49, s[0:1], 0, v45, s[0:1]
	v_add_co_u32_e64 v50, s[0:1], s65, v42
	v_add_co_u32_e32 v46, vcc, 0x5800000, v42
	s_nop 0
	v_addc_co_u32_e64 v51, s[0:1], 0, v43, s[0:1]
	v_add_co_u32_e64 v54, s[0:1], s70, v42
	v_addc_co_u32_e32 v47, vcc, 0, v43, vcc
	s_nop 0
	v_addc_co_u32_e64 v55, s[0:1], 0, v43, s[0:1]
	v_add_co_u32_e64 v56, s[0:1], s68, v44
	v_add_u32_e32 v41, s6, v4
	s_nop 0
	v_addc_co_u32_e64 v57, s[0:1], 0, v45, s[0:1]
	v_add_co_u32_e64 v58, s[0:1], s69, v44
	s_addk_i32 s6, 0x880
	s_nop 0
	v_addc_co_u32_e64 v59, s[0:1], 0, v45, s[0:1]
	v_add_co_u32_e64 v60, s[0:1], s71, v44
	v_lshl_add_u64 v[0:1], v[0:1], 0, s[8:9]
	s_nop 0
	v_addc_co_u32_e64 v61, s[0:1], 0, v45, s[0:1]
	v_add_co_u32_e64 v62, s[0:1], s72, v44
	v_lshl_add_u64 v[2:3], v[2:3], 0, s[10:11]
	s_nop 0
	v_addc_co_u32_e64 v63, s[0:1], 0, v45, s[0:1]
	v_add_co_u32_e64 v64, s[0:1], s73, v42
	v_add_co_u32_e32 v42, vcc, 0x9800000, v44
	s_nop 0
	v_addc_co_u32_e64 v65, s[0:1], 0, v43, s[0:1]
	v_add_co_u32_e64 v66, s[0:1], s74, v44
	global_load_ushort v52, v[56:57], off
	s_nop 0
	global_load_ushort v56, v[56:57], off offset:1024
	s_nop 0
	global_load_dword v57, v[54:55], off offset:-4096
	global_load_ushort v70, v[58:59], off offset:2048
	s_nop 0
	global_load_ushort v58, v[58:59], off offset:3072
	s_nop 0
	global_load_ushort v59, v[60:61], off
	s_nop 0
	global_load_ushort v60, v[60:61], off offset:1024
	s_nop 0
	global_load_dword v61, v[54:55], off
	s_nop 0
	global_load_dword v54, v[54:55], off offset:2048
	s_nop 0
	global_load_ushort v55, v[62:63], off offset:2048
	s_nop 0
	global_load_ushort v62, v[62:63], off offset:3072
	v_addc_co_u32_e64 v67, s[0:1], 0, v45, s[0:1]
	v_add_co_u32_e64 v68, s[0:1], s75, v44
	v_addc_co_u32_e32 v43, vcc, 0, v45, vcc
	s_nop 0
	v_addc_co_u32_e64 v69, s[0:1], 0, v45, s[0:1]
	global_load_ushort v63, v[66:67], off
	s_nop 0
	global_load_ushort v66, v[66:67], off offset:1024
	s_nop 0
	global_load_dword v67, v[64:65], off
	global_load_ushort v71, v[68:69], off offset:2048
	s_nop 0
	global_load_ushort v68, v[68:69], off offset:3072
	s_nop 0
	global_load_dword v64, v[64:65], off offset:2048
	global_load_dword v44, v[46:47], off
	global_load_ushort v45, v[42:43], off
	s_nop 0
	global_load_ushort v42, v[42:43], off offset:1024
	s_nop 0
	global_load_ushort v43, v[48:49], off offset:2048
	s_nop 0
	global_load_ushort v48, v[48:49], off offset:3072
	s_nop 0
	global_load_dword v49, v[50:51], off offset:2048
	s_nop 0
	global_load_dword v46, v[46:47], off offset:2048
	v_lshl_add_u64 v[80:81], s[26:27], 0, v[0:1]
	v_add_co_u32_e64 v84, s[0:1], s64, v80
	v_lshl_add_u64 v[78:79], s[26:27], 0, v[2:3]
	s_nop 0
	v_addc_co_u32_e64 v85, s[0:1], 0, v81, s[0:1]
	v_add_co_u32_e64 v86, s[0:1], s65, v78
	v_add_co_u32_e32 v82, vcc, 0x5800000, v78
	s_nop 0
	v_addc_co_u32_e64 v87, s[0:1], 0, v79, s[0:1]
	v_add_co_u32_e64 v90, s[0:1], s70, v78
	v_addc_co_u32_e32 v83, vcc, 0, v79, vcc
	s_nop 0
	v_addc_co_u32_e64 v91, s[0:1], 0, v79, s[0:1]
	v_add_co_u32_e64 v92, s[0:1], s68, v80
	v_add_u32_e32 v77, s6, v4
	s_nop 0
	v_addc_co_u32_e64 v93, s[0:1], 0, v81, s[0:1]
	v_add_co_u32_e64 v94, s[0:1], s69, v80
	s_addk_i32 s6, 0x880
	s_nop 0
	v_addc_co_u32_e64 v95, s[0:1], 0, v81, s[0:1]
	v_add_co_u32_e64 v96, s[0:1], s71, v80
	v_lshl_add_u64 v[0:1], v[0:1], 0, s[8:9]
	s_nop 0
	v_addc_co_u32_e64 v97, s[0:1], 0, v81, s[0:1]
	v_add_co_u32_e64 v98, s[0:1], s72, v80
	v_lshl_add_u64 v[2:3], v[2:3], 0, s[10:11]
	s_nop 0
	v_addc_co_u32_e64 v99, s[0:1], 0, v81, s[0:1]
	v_add_co_u32_e64 v100, s[0:1], s73, v78
	v_add_co_u32_e32 v78, vcc, 0x9800000, v80
	s_nop 0
	v_addc_co_u32_e64 v101, s[0:1], 0, v79, s[0:1]
	v_add_co_u32_e64 v102, s[0:1], s74, v80
	global_load_ushort v88, v[92:93], off
	s_nop 0
	global_load_ushort v92, v[92:93], off offset:1024
	s_nop 0
	global_load_dword v93, v[90:91], off offset:-4096
	global_load_ushort v106, v[94:95], off offset:2048
	s_nop 0
	global_load_ushort v94, v[94:95], off offset:3072
	s_nop 0
	global_load_ushort v95, v[96:97], off
	s_nop 0
	global_load_ushort v96, v[96:97], off offset:1024
	s_nop 0
	global_load_dword v97, v[90:91], off
	s_nop 0
	global_load_dword v90, v[90:91], off offset:2048
	s_nop 0
	global_load_ushort v91, v[98:99], off offset:2048
	s_nop 0
	global_load_ushort v98, v[98:99], off offset:3072
	v_addc_co_u32_e64 v103, s[0:1], 0, v81, s[0:1]
	v_add_co_u32_e64 v104, s[0:1], s75, v80
	v_addc_co_u32_e32 v79, vcc, 0, v81, vcc
	s_nop 0
	v_addc_co_u32_e64 v105, s[0:1], 0, v81, s[0:1]
	global_load_ushort v99, v[102:103], off
	s_nop 0
	global_load_ushort v102, v[102:103], off offset:1024
	s_nop 0
	global_load_dword v103, v[100:101], off
	global_load_ushort v107, v[104:105], off offset:2048
	s_nop 0
	global_load_ushort v104, v[104:105], off offset:3072
	s_nop 0
	global_load_dword v100, v[100:101], off offset:2048
	global_load_dword v80, v[82:83], off
	global_load_ushort v81, v[78:79], off
	s_nop 0
	global_load_ushort v78, v[78:79], off offset:1024
	s_nop 0
	global_load_ushort v79, v[84:85], off offset:2048
	s_nop 0
	global_load_ushort v84, v[84:85], off offset:3072
	s_nop 0
	global_load_dword v85, v[86:87], off offset:2048
	s_nop 0
	global_load_dword v82, v[82:83], off offset:2048
	v_lshl_add_u64 v[116:117], s[26:27], 0, v[0:1]
	v_add_co_u32_e64 v120, s[0:1], s64, v116
	v_lshl_add_u64 v[114:115], s[26:27], 0, v[2:3]
	s_nop 0
	v_addc_co_u32_e64 v121, s[0:1], 0, v117, s[0:1]
	v_add_co_u32_e64 v122, s[0:1], s65, v114
	v_add_co_u32_e32 v118, vcc, 0x5800000, v114
	s_nop 0
	v_addc_co_u32_e64 v123, s[0:1], 0, v115, s[0:1]
	v_add_co_u32_e64 v126, s[0:1], s70, v114
	v_addc_co_u32_e32 v119, vcc, 0, v115, vcc
	s_nop 0
	v_addc_co_u32_e64 v127, s[0:1], 0, v115, s[0:1]
	v_add_co_u32_e64 v128, s[0:1], s68, v116
	v_add_u32_e32 v113, s6, v4
	s_nop 0
	v_addc_co_u32_e64 v129, s[0:1], 0, v117, s[0:1]
	v_add_co_u32_e64 v130, s[0:1], s69, v116
	s_addk_i32 s6, 0x880
	s_nop 0
	v_addc_co_u32_e64 v131, s[0:1], 0, v117, s[0:1]
	v_add_co_u32_e64 v132, s[0:1], s71, v116
	v_lshl_add_u64 v[0:1], v[0:1], 0, s[8:9]
	s_nop 0
	v_addc_co_u32_e64 v133, s[0:1], 0, v117, s[0:1]
	v_add_co_u32_e64 v134, s[0:1], s72, v116
	v_lshl_add_u64 v[2:3], v[2:3], 0, s[10:11]
	s_nop 0
	v_addc_co_u32_e64 v135, s[0:1], 0, v117, s[0:1]
	v_add_co_u32_e64 v136, s[0:1], s73, v114
	v_add_co_u32_e32 v114, vcc, 0x9800000, v116
	s_nop 0
	v_addc_co_u32_e64 v137, s[0:1], 0, v115, s[0:1]
	v_add_co_u32_e64 v138, s[0:1], s74, v116
	global_load_ushort v124, v[128:129], off
	s_nop 0
	global_load_ushort v128, v[128:129], off offset:1024
	s_nop 0
	global_load_dword v129, v[126:127], off offset:-4096
	global_load_ushort v142, v[130:131], off offset:2048
	s_nop 0
	global_load_ushort v130, v[130:131], off offset:3072
	s_nop 0
	global_load_ushort v131, v[132:133], off
	s_nop 0
	global_load_ushort v132, v[132:133], off offset:1024
	s_nop 0
	global_load_dword v133, v[126:127], off
	s_nop 0
	global_load_dword v126, v[126:127], off offset:2048
	s_nop 0
	global_load_ushort v127, v[134:135], off offset:2048
	s_nop 0
	global_load_ushort v134, v[134:135], off offset:3072
	v_addc_co_u32_e64 v139, s[0:1], 0, v117, s[0:1]
	v_add_co_u32_e64 v140, s[0:1], s75, v116
	v_addc_co_u32_e32 v115, vcc, 0, v117, vcc
	s_nop 0
	v_addc_co_u32_e64 v141, s[0:1], 0, v117, s[0:1]
	global_load_ushort v135, v[138:139], off
	s_nop 0
	global_load_ushort v138, v[138:139], off offset:1024
	s_nop 0
	global_load_dword v139, v[136:137], off
	global_load_ushort v143, v[140:141], off offset:2048
	s_nop 0
	global_load_ushort v140, v[140:141], off offset:3072
	s_nop 0
	global_load_dword v136, v[136:137], off offset:2048
	global_load_dword v116, v[118:119], off
	global_load_ushort v117, v[114:115], off
	s_nop 0
	global_load_ushort v114, v[114:115], off offset:1024
	s_nop 0
	global_load_ushort v115, v[120:121], off offset:2048
	s_nop 0
	global_load_ushort v120, v[120:121], off offset:3072
	s_nop 0
	global_load_dword v121, v[122:123], off offset:2048
	s_nop 0
	global_load_dword v118, v[118:119], off offset:2048
	s_waitcnt vmcnt(63)
	v_lshlrev_b32_e32 v11, 16, v16
	s_waitcnt vmcnt(63)
	v_lshlrev_b32_e32 v14, 16, v20
	s_waitcnt vmcnt(63)
	v_mul_f32_e32 v15, 0x3fb8aa3b, v21
	v_mul_f32_e32 v16, 0xbfb8aa3b, v21
	s_waitcnt vmcnt(63)
	v_lshlrev_b32_e32 v21, 16, v22
	s_waitcnt vmcnt(63)
	v_lshlrev_b32_e32 v22, 16, v23
	s_waitcnt vmcnt(63)
	v_lshlrev_b32_e32 v23, 16, v24
	s_waitcnt vmcnt(63)
	v_mul_f32_e32 v24, 0x3fb8aa3b, v25
	v_lshlrev_b32_e32 v20, 16, v34
	v_mul_f32_e32 v25, 0xbfb8aa3b, v25
	s_waitcnt vmcnt(63)
	v_mul_f32_e32 v29, 0x3fb8aa3b, v18
	v_mul_f32_e32 v18, 0xbfb8aa3b, v18
	v_exp_f32_e32 v15, v15
	v_exp_f32_e32 v16, v16
	v_exp_f32_e32 v24, v24
	v_exp_f32_e32 v25, v25
	s_waitcnt vmcnt(63)
	v_mul_f32_e32 v33, 0x3fb8aa3b, v31
	v_mul_f32_e32 v31, 0xbfb8aa3b, v31
	s_waitcnt vmcnt(63)
	v_lshlrev_b32_e32 v34, 16, v35
	s_waitcnt vmcnt(63)
	v_mul_f32_e32 v35, 0x3fb8aa3b, v28
	v_mul_f32_e32 v28, 0xbfb8aa3b, v28
	s_waitcnt vmcnt(63)
	v_mul_f32_e32 v36, 0x3fb8aa3b, v8
	v_mul_f32_e32 v8, 0xbfb8aa3b, v8
	v_exp_f32_e32 v8, v8
	s_waitcnt vmcnt(63)
	v_mul_f32_e32 v37, 0x3fb8aa3b, v10
	v_exp_f32_e32 v29, v29
	v_exp_f32_e32 v18, v18
	v_exp_f32_e32 v33, v33
	v_exp_f32_e32 v31, v31
	v_exp_f32_e32 v35, v35
	v_exp_f32_e32 v28, v28
	v_exp_f32_e32 v36, v36
	v_mul_f32_e32 v10, 0xbfb8aa3b, v10
	v_mul_f32_e32 v38, 0x3fb8aa3b, v13
	v_mul_f32_e32 v13, 0xbfb8aa3b, v13
	v_exp_f32_e32 v37, v37
	v_exp_f32_e32 v10, v10
	v_exp_f32_e32 v38, v38
	v_exp_f32_e32 v13, v13
	v_lshlrev_b32_e32 v19, 16, v19
	v_lshlrev_b32_e32 v27, 16, v27
	v_mul_f32_e32 v11, 0x3db504f3, v11
	v_mul_f32_e32 v22, 0x3db504f3, v22
	v_lshlrev_b32_e32 v9, 16, v9
	v_lshlrev_b32_e32 v6, 16, v6
	v_lshlrev_b32_e32 v7, 16, v7
	v_lshlrev_b32_e32 v26, 16, v26
	v_lshlrev_b32_e32 v30, 16, v30
	v_lshlrev_b32_e32 v32, 16, v32
	v_mul_f32_e32 v19, 0x3db504f3, v19
	v_mul_f32_e32 v27, 0x3db504f3, v27
	v_mul_f32_e32 v34, 0x3db504f3, v34
	v_mul_f32_e32 v9, 0x3db504f3, v9
	v_mul_f32_e32 v7, 0x3db504f3, v7
	v_mul_f32_e32 v11, v15, v11
	v_mul_f32_e32 v14, v16, v14
	v_mul_f32_e32 v15, v24, v22
	v_mul_f32_e32 v6, v8, v6
	v_mul_f32_e32 v20, 0x3db504f3, v20
	v_lshlrev_b32_e32 v12, 16, v12
	v_mul_f32_e32 v16, v25, v23
	v_mul_f32_e32 v19, v29, v19
	v_mul_f32_e32 v18, v18, v26
	v_mul_f32_e32 v22, v33, v27
	v_mul_f32_e32 v23, v31, v30
	v_mul_f32_e32 v24, v35, v34
	v_mul_f32_e32 v25, v28, v32
	v_mul_f32_e32 v9, v36, v9
	v_cvt_pk_bf16_f32 v8, v11, s0
	v_cvt_pk_bf16_f32 v11, v14, s0
	v_cvt_pk_bf16_f32 v14, v15, s0
	v_cvt_pk_bf16_f32 v6, v6, s0
	v_mul_f32_e32 v7, v37, v7
	v_cvt_pk_bf16_f32 v15, v16, s0
	v_cvt_pk_bf16_f32 v16, v19, s0
	v_cvt_pk_bf16_f32 v18, v18, s0
	v_cvt_pk_bf16_f32 v19, v22, s0
	v_cvt_pk_bf16_f32 v22, v23, s0
	v_cvt_pk_bf16_f32 v23, v24, s0
	v_cvt_pk_bf16_f32 v24, v25, s0
	v_cvt_pk_bf16_f32 v9, v9, s0
	v_mul_f32_e32 v10, v10, v12
	ds_write_b16 v5, v8 offset:544
	ds_write_b16 v5, v11 offset:17952
	v_mul_f32_e32 v8, v38, v20
	v_mul_f32_e32 v11, v13, v21
	ds_write_b16 v5, v14 offset:1088
	ds_write_b16 v5, v15 offset:18496
	ds_write_b16 v5, v16 offset:1360
	ds_write_b16 v5, v18 offset:18768
	ds_write_b16 v5, v19 offset:1632
	ds_write_b16 v5, v22 offset:19040
	ds_write_b16 v5, v23 offset:1904
	ds_write_b16 v5, v24 offset:19312
	ds_write_b16 v5, v9
	ds_write_b16 v5, v6 offset:17408
	v_cvt_pk_bf16_f32 v6, v7, s0
	v_cvt_pk_bf16_f32 v7, v10, s0
	v_cvt_pk_bf16_f32 v8, v8, s0
	v_cvt_pk_bf16_f32 v9, v11, s0
	ds_write_b16 v5, v6 offset:272
	ds_write_b16 v5, v7 offset:17680
	ds_write_b16 v5, v8 offset:816
	ds_write_b16 v5, v9 offset:18224
	s_waitcnt vmcnt(63)
	v_lshlrev_b32_e32 v47, 16, v52
	s_waitcnt vmcnt(63)
	v_lshlrev_b32_e32 v50, 16, v56
	s_waitcnt vmcnt(63)
	v_mul_f32_e32 v51, 0x3fb8aa3b, v57
	v_mul_f32_e32 v52, 0xbfb8aa3b, v57
	s_waitcnt vmcnt(63)
	v_lshlrev_b32_e32 v57, 16, v58
	s_waitcnt vmcnt(63)
	v_lshlrev_b32_e32 v58, 16, v59
	s_waitcnt vmcnt(63)
	v_lshlrev_b32_e32 v59, 16, v60
	s_waitcnt vmcnt(63)
	v_mul_f32_e32 v60, 0x3fb8aa3b, v61
	v_lshlrev_b32_e32 v56, 16, v70
	v_mul_f32_e32 v61, 0xbfb8aa3b, v61
	s_waitcnt vmcnt(63)
	v_mul_f32_e32 v65, 0x3fb8aa3b, v54
	v_mul_f32_e32 v54, 0xbfb8aa3b, v54
	v_exp_f32_e32 v51, v51
	v_exp_f32_e32 v52, v52
	v_exp_f32_e32 v60, v60
	v_exp_f32_e32 v61, v61
	s_waitcnt vmcnt(58)
	v_mul_f32_e32 v69, 0x3fb8aa3b, v67
	v_mul_f32_e32 v67, 0xbfb8aa3b, v67
	s_waitcnt vmcnt(57)
	v_lshlrev_b32_e32 v70, 16, v71
	s_waitcnt vmcnt(55)
	v_mul_f32_e32 v71, 0x3fb8aa3b, v64
	v_mul_f32_e32 v64, 0xbfb8aa3b, v64
	s_waitcnt vmcnt(54)
	v_mul_f32_e32 v72, 0x3fb8aa3b, v44
	v_mul_f32_e32 v44, 0xbfb8aa3b, v44
	v_exp_f32_e32 v44, v44
	s_waitcnt vmcnt(48)
	v_mul_f32_e32 v73, 0x3fb8aa3b, v46
	v_exp_f32_e32 v65, v65
	v_exp_f32_e32 v54, v54
	v_exp_f32_e32 v69, v69
	v_exp_f32_e32 v67, v67
	v_exp_f32_e32 v71, v71
	v_exp_f32_e32 v64, v64
	v_exp_f32_e32 v72, v72
	v_mul_f32_e32 v46, 0xbfb8aa3b, v46
	v_mul_f32_e32 v74, 0x3fb8aa3b, v49
	v_mul_f32_e32 v49, 0xbfb8aa3b, v49
	v_exp_f32_e32 v73, v73
	v_exp_f32_e32 v46, v46
	v_exp_f32_e32 v74, v74
	v_exp_f32_e32 v49, v49
	v_lshlrev_b32_e32 v55, 16, v55
	v_lshlrev_b32_e32 v63, 16, v63
	v_mul_f32_e32 v47, 0x3db504f3, v47
	v_mul_f32_e32 v58, 0x3db504f3, v58
	v_lshlrev_b32_e32 v45, 16, v45
	v_lshlrev_b32_e32 v42, 16, v42
	v_lshlrev_b32_e32 v43, 16, v43
	v_lshlrev_b32_e32 v62, 16, v62
	v_lshlrev_b32_e32 v66, 16, v66
	v_lshlrev_b32_e32 v68, 16, v68
	v_mul_f32_e32 v55, 0x3db504f3, v55
	v_mul_f32_e32 v63, 0x3db504f3, v63
	v_mul_f32_e32 v70, 0x3db504f3, v70
	v_mul_f32_e32 v45, 0x3db504f3, v45
	v_mul_f32_e32 v43, 0x3db504f3, v43
	v_mul_f32_e32 v47, v51, v47
	v_mul_f32_e32 v50, v52, v50
	v_mul_f32_e32 v51, v60, v58
	v_mul_f32_e32 v42, v44, v42
	v_mul_f32_e32 v56, 0x3db504f3, v56
	v_lshlrev_b32_e32 v48, 16, v48
	v_mul_f32_e32 v52, v61, v59
	v_mul_f32_e32 v55, v65, v55
	v_mul_f32_e32 v54, v54, v62
	v_mul_f32_e32 v58, v69, v63
	v_mul_f32_e32 v59, v67, v66
	v_mul_f32_e32 v60, v71, v70
	v_mul_f32_e32 v61, v64, v68
	v_mul_f32_e32 v45, v72, v45
	v_cvt_pk_bf16_f32 v44, v47, s0
	v_cvt_pk_bf16_f32 v47, v50, s0
	v_cvt_pk_bf16_f32 v50, v51, s0
	v_cvt_pk_bf16_f32 v42, v42, s0
	v_mul_f32_e32 v43, v73, v43
	v_cvt_pk_bf16_f32 v51, v52, s0
	v_cvt_pk_bf16_f32 v52, v55, s0
	v_cvt_pk_bf16_f32 v54, v54, s0
	v_cvt_pk_bf16_f32 v55, v58, s0
	v_cvt_pk_bf16_f32 v58, v59, s0
	v_cvt_pk_bf16_f32 v59, v60, s0
	v_cvt_pk_bf16_f32 v60, v61, s0
	v_cvt_pk_bf16_f32 v45, v45, s0
	v_mul_f32_e32 v46, v46, v48
	ds_write_b16 v41, v44 offset:544
	ds_write_b16 v41, v47 offset:17952
	v_mul_f32_e32 v44, v74, v56
	v_mul_f32_e32 v47, v49, v57
	ds_write_b16 v41, v50 offset:1088
	ds_write_b16 v41, v51 offset:18496
	ds_write_b16 v41, v52 offset:1360
	ds_write_b16 v41, v54 offset:18768
	ds_write_b16 v41, v55 offset:1632
	ds_write_b16 v41, v58 offset:19040
	ds_write_b16 v41, v59 offset:1904
	ds_write_b16 v41, v60 offset:19312
	ds_write_b16 v41, v45
	ds_write_b16 v41, v42 offset:17408
	v_cvt_pk_bf16_f32 v42, v43, s0
	v_cvt_pk_bf16_f32 v43, v46, s0
	v_cvt_pk_bf16_f32 v44, v44, s0
	v_cvt_pk_bf16_f32 v45, v47, s0
	ds_write_b16 v41, v42 offset:272
	ds_write_b16 v41, v43 offset:17680
	ds_write_b16 v41, v44 offset:816
	ds_write_b16 v41, v45 offset:18224
	s_waitcnt vmcnt(47)
	v_lshlrev_b32_e32 v83, 16, v88
	s_waitcnt vmcnt(46)
	v_lshlrev_b32_e32 v86, 16, v92
	s_waitcnt vmcnt(45)
	v_mul_f32_e32 v87, 0x3fb8aa3b, v93
	v_mul_f32_e32 v88, 0xbfb8aa3b, v93
	s_waitcnt vmcnt(43)
	v_lshlrev_b32_e32 v93, 16, v94
	s_waitcnt vmcnt(42)
	v_lshlrev_b32_e32 v94, 16, v95
	s_waitcnt vmcnt(41)
	v_lshlrev_b32_e32 v95, 16, v96
	s_waitcnt vmcnt(40)
	v_mul_f32_e32 v96, 0x3fb8aa3b, v97
	v_lshlrev_b32_e32 v92, 16, v106
	v_mul_f32_e32 v97, 0xbfb8aa3b, v97
	s_waitcnt vmcnt(39)
	v_mul_f32_e32 v101, 0x3fb8aa3b, v90
	v_mul_f32_e32 v90, 0xbfb8aa3b, v90
	v_exp_f32_e32 v87, v87
	v_exp_f32_e32 v88, v88
	v_exp_f32_e32 v96, v96
	v_exp_f32_e32 v97, v97
	s_waitcnt vmcnt(34)
	v_mul_f32_e32 v105, 0x3fb8aa3b, v103
	v_mul_f32_e32 v103, 0xbfb8aa3b, v103
	s_waitcnt vmcnt(33)
	v_lshlrev_b32_e32 v106, 16, v107
	s_waitcnt vmcnt(31)
	v_mul_f32_e32 v107, 0x3fb8aa3b, v100
	v_mul_f32_e32 v100, 0xbfb8aa3b, v100
	s_waitcnt vmcnt(30)
	v_mul_f32_e32 v108, 0x3fb8aa3b, v80
	v_mul_f32_e32 v80, 0xbfb8aa3b, v80
	v_exp_f32_e32 v80, v80
	s_waitcnt vmcnt(24)
	v_mul_f32_e32 v109, 0x3fb8aa3b, v82
	v_exp_f32_e32 v101, v101
	v_exp_f32_e32 v90, v90
	v_exp_f32_e32 v105, v105
	v_exp_f32_e32 v103, v103
	v_exp_f32_e32 v107, v107
	v_exp_f32_e32 v100, v100
	v_exp_f32_e32 v108, v108
	v_mul_f32_e32 v82, 0xbfb8aa3b, v82
	v_mul_f32_e32 v110, 0x3fb8aa3b, v85
	v_mul_f32_e32 v85, 0xbfb8aa3b, v85
	v_exp_f32_e32 v109, v109
	v_exp_f32_e32 v82, v82
	v_exp_f32_e32 v110, v110
	v_exp_f32_e32 v85, v85
	v_lshlrev_b32_e32 v91, 16, v91
	v_lshlrev_b32_e32 v99, 16, v99
	v_mul_f32_e32 v83, 0x3db504f3, v83
	v_mul_f32_e32 v94, 0x3db504f3, v94
	v_lshlrev_b32_e32 v81, 16, v81
	v_lshlrev_b32_e32 v78, 16, v78
	v_lshlrev_b32_e32 v79, 16, v79
	v_lshlrev_b32_e32 v98, 16, v98
	v_lshlrev_b32_e32 v102, 16, v102
	v_lshlrev_b32_e32 v104, 16, v104
	v_mul_f32_e32 v91, 0x3db504f3, v91
	v_mul_f32_e32 v99, 0x3db504f3, v99
	v_mul_f32_e32 v106, 0x3db504f3, v106
	v_mul_f32_e32 v81, 0x3db504f3, v81
	v_mul_f32_e32 v79, 0x3db504f3, v79
	v_mul_f32_e32 v83, v87, v83
	v_mul_f32_e32 v86, v88, v86
	v_mul_f32_e32 v87, v96, v94
	v_mul_f32_e32 v78, v80, v78
	v_mul_f32_e32 v92, 0x3db504f3, v92
	v_lshlrev_b32_e32 v84, 16, v84
	v_mul_f32_e32 v88, v97, v95
	v_mul_f32_e32 v91, v101, v91
	v_mul_f32_e32 v90, v90, v98
	v_mul_f32_e32 v94, v105, v99
	v_mul_f32_e32 v95, v103, v102
	v_mul_f32_e32 v96, v107, v106
	v_mul_f32_e32 v97, v100, v104
	v_mul_f32_e32 v81, v108, v81
	v_cvt_pk_bf16_f32 v80, v83, s0
	v_cvt_pk_bf16_f32 v83, v86, s0
	v_cvt_pk_bf16_f32 v86, v87, s0
	v_cvt_pk_bf16_f32 v78, v78, s0
	v_mul_f32_e32 v79, v109, v79
	v_cvt_pk_bf16_f32 v87, v88, s0
	v_cvt_pk_bf16_f32 v88, v91, s0
	v_cvt_pk_bf16_f32 v90, v90, s0
	v_cvt_pk_bf16_f32 v91, v94, s0
	v_cvt_pk_bf16_f32 v94, v95, s0
	v_cvt_pk_bf16_f32 v95, v96, s0
	v_cvt_pk_bf16_f32 v96, v97, s0
	v_cvt_pk_bf16_f32 v81, v81, s0
	v_mul_f32_e32 v82, v82, v84
	ds_write_b16 v77, v80 offset:544
	ds_write_b16 v77, v83 offset:17952
	v_mul_f32_e32 v80, v110, v92
	v_mul_f32_e32 v83, v85, v93
	ds_write_b16 v77, v86 offset:1088
	ds_write_b16 v77, v87 offset:18496
	ds_write_b16 v77, v88 offset:1360
	ds_write_b16 v77, v90 offset:18768
	ds_write_b16 v77, v91 offset:1632
	ds_write_b16 v77, v94 offset:19040
	ds_write_b16 v77, v95 offset:1904
	ds_write_b16 v77, v96 offset:19312
	ds_write_b16 v77, v81
	ds_write_b16 v77, v78 offset:17408
	v_cvt_pk_bf16_f32 v78, v79, s0
	v_cvt_pk_bf16_f32 v79, v82, s0
	v_cvt_pk_bf16_f32 v80, v80, s0
	v_cvt_pk_bf16_f32 v81, v83, s0
	ds_write_b16 v77, v78 offset:272
	ds_write_b16 v77, v79 offset:17680
	ds_write_b16 v77, v80 offset:816
	ds_write_b16 v77, v81 offset:18224
	s_waitcnt vmcnt(23)
	v_lshlrev_b32_e32 v119, 16, v124
	s_waitcnt vmcnt(22)
	v_lshlrev_b32_e32 v122, 16, v128
	s_waitcnt vmcnt(21)
	v_mul_f32_e32 v123, 0x3fb8aa3b, v129
	v_mul_f32_e32 v124, 0xbfb8aa3b, v129
	s_waitcnt vmcnt(19)
	v_lshlrev_b32_e32 v129, 16, v130
	s_waitcnt vmcnt(18)
	v_lshlrev_b32_e32 v130, 16, v131
	s_waitcnt vmcnt(17)
	v_lshlrev_b32_e32 v131, 16, v132
	s_waitcnt vmcnt(16)
	v_mul_f32_e32 v132, 0x3fb8aa3b, v133
	v_lshlrev_b32_e32 v128, 16, v142
	v_mul_f32_e32 v133, 0xbfb8aa3b, v133
	s_waitcnt vmcnt(15)
	v_mul_f32_e32 v137, 0x3fb8aa3b, v126
	v_mul_f32_e32 v126, 0xbfb8aa3b, v126
	v_exp_f32_e32 v123, v123
	v_exp_f32_e32 v124, v124
	v_exp_f32_e32 v132, v132
	v_exp_f32_e32 v133, v133
	s_waitcnt vmcnt(10)
	v_mul_f32_e32 v141, 0x3fb8aa3b, v139
	v_mul_f32_e32 v139, 0xbfb8aa3b, v139
	s_waitcnt vmcnt(9)
	v_lshlrev_b32_e32 v142, 16, v143
	s_waitcnt vmcnt(7)
	v_mul_f32_e32 v143, 0x3fb8aa3b, v136
	v_mul_f32_e32 v136, 0xbfb8aa3b, v136
	s_waitcnt vmcnt(6)
	v_mul_f32_e32 v144, 0x3fb8aa3b, v116
	v_mul_f32_e32 v116, 0xbfb8aa3b, v116
	v_exp_f32_e32 v116, v116
	s_waitcnt vmcnt(0)
	v_mul_f32_e32 v145, 0x3fb8aa3b, v118
	v_exp_f32_e32 v137, v137
	v_exp_f32_e32 v126, v126
	v_exp_f32_e32 v141, v141
	v_exp_f32_e32 v139, v139
	v_exp_f32_e32 v143, v143
	v_exp_f32_e32 v136, v136
	v_exp_f32_e32 v144, v144
	v_mul_f32_e32 v118, 0xbfb8aa3b, v118
	v_mul_f32_e32 v146, 0x3fb8aa3b, v121
	v_mul_f32_e32 v121, 0xbfb8aa3b, v121
	v_exp_f32_e32 v145, v145
	v_exp_f32_e32 v118, v118
	v_exp_f32_e32 v146, v146
	v_exp_f32_e32 v121, v121
	v_lshlrev_b32_e32 v127, 16, v127
	v_lshlrev_b32_e32 v135, 16, v135
	v_mul_f32_e32 v119, 0x3db504f3, v119
	v_mul_f32_e32 v130, 0x3db504f3, v130
	v_lshlrev_b32_e32 v117, 16, v117
	v_lshlrev_b32_e32 v114, 16, v114
	v_lshlrev_b32_e32 v115, 16, v115
	v_lshlrev_b32_e32 v134, 16, v134
	v_lshlrev_b32_e32 v138, 16, v138
	v_lshlrev_b32_e32 v140, 16, v140
	v_mul_f32_e32 v127, 0x3db504f3, v127
	v_mul_f32_e32 v135, 0x3db504f3, v135
	v_mul_f32_e32 v142, 0x3db504f3, v142
	v_mul_f32_e32 v117, 0x3db504f3, v117
	v_mul_f32_e32 v115, 0x3db504f3, v115
	v_mul_f32_e32 v119, v123, v119
	v_mul_f32_e32 v122, v124, v122
	v_mul_f32_e32 v123, v132, v130
	v_mul_f32_e32 v114, v116, v114
	v_mul_f32_e32 v128, 0x3db504f3, v128
	v_lshlrev_b32_e32 v120, 16, v120
	v_mul_f32_e32 v124, v133, v131
	v_mul_f32_e32 v127, v137, v127
	v_mul_f32_e32 v126, v126, v134
	v_mul_f32_e32 v130, v141, v135
	v_mul_f32_e32 v131, v139, v138
	v_mul_f32_e32 v132, v143, v142
	v_mul_f32_e32 v133, v136, v140
	v_mul_f32_e32 v117, v144, v117
	v_cvt_pk_bf16_f32 v116, v119, s0
	v_cvt_pk_bf16_f32 v119, v122, s0
	v_cvt_pk_bf16_f32 v122, v123, s0
	v_cvt_pk_bf16_f32 v114, v114, s0
	v_mul_f32_e32 v115, v145, v115
	v_cvt_pk_bf16_f32 v123, v124, s0
	v_cvt_pk_bf16_f32 v124, v127, s0
	v_cvt_pk_bf16_f32 v126, v126, s0
	v_cvt_pk_bf16_f32 v127, v130, s0
	v_cvt_pk_bf16_f32 v130, v131, s0
	v_cvt_pk_bf16_f32 v131, v132, s0
	v_cvt_pk_bf16_f32 v132, v133, s0
	v_cvt_pk_bf16_f32 v117, v117, s0
	v_mul_f32_e32 v118, v118, v120
	ds_write_b16 v113, v116 offset:544
	ds_write_b16 v113, v119 offset:17952
	v_mul_f32_e32 v116, v146, v128
	v_mul_f32_e32 v119, v121, v129
	ds_write_b16 v113, v122 offset:1088
	ds_write_b16 v113, v123 offset:18496
	ds_write_b16 v113, v124 offset:1360
	ds_write_b16 v113, v126 offset:18768
	ds_write_b16 v113, v127 offset:1632
	ds_write_b16 v113, v130 offset:19040
	ds_write_b16 v113, v131 offset:1904
	ds_write_b16 v113, v132 offset:19312
	ds_write_b16 v113, v117
	ds_write_b16 v113, v114 offset:17408
	v_cvt_pk_bf16_f32 v114, v115, s0
	v_cvt_pk_bf16_f32 v115, v118, s0
	v_cvt_pk_bf16_f32 v116, v116, s0
	v_cvt_pk_bf16_f32 v117, v119, s0
	ds_write_b16 v113, v114 offset:272
	ds_write_b16 v113, v115 offset:17680
	ds_write_b16 v113, v116 offset:816
	ds_write_b16 v113, v117 offset:18224
	v_and_b32_e32 v182, 31, v180
	v_bfe_u32 v181, v180, 5, 1
	v_or_b32_e32 v0, v17, v182
	v_lshlrev_b32_e32 v16, 4, v181
	v_mad_u64_u32 v[34:35], s[0:1], v0, s76, v[16:17]
	s_waitcnt lgkmcnt(0)
	s_barrier
	ds_read_b128 v[0:3], v34 offset:5120
	v_ashrrev_i32_e32 v35, 1, v180
	v_and_or_b32 v36, v35, 32, v182
	v_mad_u32_u24 v37, v36, s76, v16
	ds_read_b128 v[4:7], v37 offset:22528
	ds_read_b128 v[18:21], v34 offset:5152
	ds_read_b128 v[22:25], v37 offset:22560
	s_waitcnt lgkmcnt(2)
	v_mfma_f32_32x32x16_bf16 v[0:15], v[0:3], v[4:7], 0
	s_and_b32 s0, s16, 3
	v_lshl_or_b32 v17, v181, 2, v17
	v_or_b32_e32 v41, 1, v17
	v_cmp_le_i32_e32 vcc, v36, v17
	v_mul_u32_u24_e32 v38, 0x110, v36
	v_mul_i32_i24_e32 v39, 0xfffffef2, v36
	v_mul_lo_u32 v40, v17, s77
	s_waitcnt lgkmcnt(0)
	v_mfma_f32_32x32x16_bf16 v[0:15], v[18:21], v[22:25], v[0:15]
	ds_read_b128 v[18:21], v34 offset:5184
	ds_read_b128 v[22:25], v37 offset:22592
	ds_read_b128 v[26:29], v34 offset:5216
	ds_read_b128 v[30:33], v37 offset:22624
	s_lshl_b32 s1, s16, 4
	s_andn2_b32 s1, s1, 63
	s_lshl_b32 s6, s0, 9
	s_ashr_i32 s17, s16, 31
	v_mad_u32_u24 v200, v182, s77, v16
	s_waitcnt lgkmcnt(2)
	v_mfma_f32_32x32x16_bf16 v[0:15], v[18:21], v[22:25], v[0:15]
	s_waitcnt lgkmcnt(0)
	v_mfma_f32_32x32x16_bf16 v[0:15], v[26:29], v[30:33], v[0:15]
	ds_read_b128 v[18:21], v34 offset:5248
	ds_read_b128 v[22:25], v37 offset:22656
	ds_read_b128 v[26:29], v34 offset:5280
	ds_read_b128 v[30:33], v37 offset:22688
	s_waitcnt lgkmcnt(2)
	v_mfma_f32_32x32x16_bf16 v[0:15], v[18:21], v[22:25], v[0:15]
	ds_read_b128 v[18:21], v34 offset:5312
	ds_read_b128 v[22:25], v37 offset:22720
	s_waitcnt lgkmcnt(2)
	v_mfma_f32_32x32x16_bf16 v[0:15], v[26:29], v[30:33], v[0:15]
	ds_read_b128 v[26:29], v34 offset:5344
	ds_read_b128 v[30:33], v37 offset:22752
	s_waitcnt lgkmcnt(2)
	v_mfma_f32_32x32x16_bf16 v[0:15], v[18:21], v[22:25], v[0:15]
	v_or_b32_e32 v18, 2, v17
	v_or_b32_e32 v19, 3, v17
	v_or_b32_e32 v20, 8, v17
	v_or_b32_e32 v21, 9, v17
	v_or_b32_e32 v22, 10, v17
	v_or_b32_e32 v23, 11, v17
	v_add3_u32 v24, v38, v39, v40
	s_waitcnt lgkmcnt(0)
	v_mfma_f32_32x32x16_bf16 v[0:15], v[26:29], v[30:33], v[0:15]
	s_nop 11
	v_cvt_pk_bf16_f32 v0, v0, s0
	v_cvt_pk_bf16_f32 v1, v1, s0
	v_cndmask_b32_e32 v0, 0, v0, vcc
	v_cmp_le_i32_e32 vcc, v36, v41
	v_cvt_pk_bf16_f32 v2, v2, s0
	v_cvt_pk_bf16_f32 v3, v3, s0
	v_cndmask_b32_e32 v1, 0, v1, vcc
	v_cmp_le_i32_e32 vcc, v36, v18
	v_cvt_pk_bf16_f32 v4, v4, s0
	v_cvt_pk_bf16_f32 v5, v5, s0
	v_cndmask_b32_e32 v2, 0, v2, vcc
	v_cmp_le_i32_e32 vcc, v36, v19
	v_cvt_pk_bf16_f32 v6, v6, s0
	s_nop 0
	v_cndmask_b32_e32 v3, 0, v3, vcc
	v_cmp_le_i32_e32 vcc, v36, v20
	s_nop 1
	v_cndmask_b32_e32 v4, 0, v4, vcc
	v_cmp_le_i32_e32 vcc, v36, v21
	s_nop 1
	v_cndmask_b32_e32 v5, 0, v5, vcc
	v_cmp_le_i32_e32 vcc, v36, v22
	s_nop 1
	v_cndmask_b32_e32 v6, 0, v6, vcc
	ds_write_b16 v24, v0 offset:39936
	ds_write_b16 v24, v1 offset:40080
	ds_write_b16 v24, v2 offset:40224
	ds_write_b16 v24, v3 offset:40368
	ds_write_b16 v24, v4 offset:41088
	ds_write_b16 v24, v5 offset:41232
	ds_write_b16 v24, v6 offset:41376
	v_cvt_pk_bf16_f32 v0, v7, s0
	v_cmp_le_i32_e32 vcc, v36, v23
	v_cvt_pk_bf16_f32 v1, v8, s0
	s_nop 0
	v_cndmask_b32_e32 v0, 0, v0, vcc
	ds_write_b16 v24, v0 offset:41520
	v_or_b32_e32 v0, 16, v17
	v_cmp_le_i32_e32 vcc, v36, v0
	s_nop 1
	v_cndmask_b32_e32 v0, 0, v1, vcc
	ds_write_b16 v24, v0 offset:42240
	v_or_b32_e32 v0, 17, v17
	v_cvt_pk_bf16_f32 v1, v9, s0
	v_cmp_le_i32_e32 vcc, v36, v0
	s_nop 1
	v_cndmask_b32_e32 v0, 0, v1, vcc
	ds_write_b16 v24, v0 offset:42384
	v_or_b32_e32 v0, 18, v17
	v_cvt_pk_bf16_f32 v1, v10, s0
	v_cmp_le_i32_e32 vcc, v36, v0
	s_nop 1
	v_cndmask_b32_e32 v0, 0, v1, vcc
	ds_write_b16 v24, v0 offset:42528
	v_or_b32_e32 v0, 19, v17
	v_cvt_pk_bf16_f32 v1, v11, s0
	v_cmp_le_i32_e32 vcc, v36, v0
	s_nop 1
	v_cndmask_b32_e32 v0, 0, v1, vcc
	ds_write_b16 v24, v0 offset:42672
	v_or_b32_e32 v0, 24, v17
	v_cvt_pk_bf16_f32 v1, v12, s0
	v_cmp_le_i32_e32 vcc, v36, v0
	s_nop 1
	v_cndmask_b32_e32 v0, 0, v1, vcc
	ds_write_b16 v24, v0 offset:43392
	v_or_b32_e32 v0, 25, v17
	v_cvt_pk_bf16_f32 v1, v13, s0
	v_cmp_le_i32_e32 vcc, v36, v0
	s_nop 1
	v_cndmask_b32_e32 v0, 0, v1, vcc
	ds_write_b16 v24, v0 offset:43536
	v_or_b32_e32 v0, 26, v17
	v_cvt_pk_bf16_f32 v1, v14, s0
	v_cmp_le_i32_e32 vcc, v36, v0
	s_nop 1
	v_cndmask_b32_e32 v0, 0, v1, vcc
	ds_write_b16 v24, v0 offset:43680
	v_or_b32_e32 v0, 27, v17
	v_cvt_pk_bf16_f32 v1, v15, s0
	v_cmp_le_i32_e32 vcc, v36, v0
	s_nop 1
	v_cndmask_b32_e32 v0, 0, v1, vcc
	ds_write_b16 v24, v0 offset:43824
	v_mov_b32_e32 v0, v205
	s_waitcnt lgkmcnt(0)
	s_barrier
	s_nop 0
	v_ashrrev_i32_e32 v1, 2, v0
	v_and_b32_e32 v17, 0xffffffe0, v1
	v_add_u32_e32 v19, s1, v17
	v_or_b32_e32 v20, 4, v17
	v_or_b32_e32 v12, 6, v19
	v_or_b32_e32 v10, 5, v19
	v_add_u32_e32 v8, s1, v20
	v_and_b32_e32 v18, 0x7f, v0
	v_or_b32_e32 v6, 3, v19
	v_or_b32_e32 v4, 2, v19
	v_or_b32_e32 v2, 1, v19
	v_mad_i64_i32 v[0:1], s[86:87], v19, s49, v[164:165]
	v_or_b32_e32 v14, 7, v19
	v_mad_i64_i32 v[8:9], s[86:87], v8, s49, v[164:165]
	v_mad_i64_i32 v[10:11], s[86:87], v10, s49, v[164:165]
	v_mad_i64_i32 v[12:13], s[86:87], v12, s49, v[164:165]
	v_mad_i64_i32 v[2:3], s[86:87], v2, s49, v[164:165]
	v_mad_i64_i32 v[4:5], s[86:87], v4, s49, v[164:165]
	v_mad_i64_i32 v[6:7], s[86:87], v6, s49, v[164:165]
	v_lshl_add_u64 v[0:1], v[0:1], 0, s[6:7]
	v_lshlrev_b32_e32 v166, 1, v18
	v_mad_i64_i32 v[14:15], s[86:87], v14, s49, v[164:165]
	v_lshl_add_u64 v[8:9], v[8:9], 0, s[6:7]
	v_lshl_add_u64 v[10:11], v[10:11], 0, s[6:7]
	v_lshl_add_u64 v[12:13], v[12:13], 0, s[6:7]
	v_lshl_add_u64 v[2:3], v[2:3], 0, s[6:7]
	v_lshl_add_u64 v[4:5], v[4:5], 0, s[6:7]
	v_lshl_add_u64 v[6:7], v[6:7], 0, s[6:7]
	v_lshl_add_u64 v[0:1], v[0:1], 0, v[166:167]
	v_lshl_add_u64 v[14:15], v[14:15], 0, s[6:7]
	v_lshl_add_u64 v[8:9], v[8:9], 0, v[166:167]
	v_lshl_add_u64 v[10:11], v[10:11], 0, v[166:167]
	v_lshl_add_u64 v[12:13], v[12:13], 0, v[166:167]
	v_or_b32_e32 v29, 8, v17
	v_or_b32_e32 v30, 12, v17
	v_lshl_add_u64 v[2:3], v[2:3], 0, v[166:167]
	v_lshl_add_u64 v[4:5], v[4:5], 0, v[166:167]
	v_lshl_add_u64 v[6:7], v[6:7], 0, v[166:167]
	v_lshl_add_u64 v[14:15], v[14:15], 0, v[166:167]
	global_load_ushort v21, v[0:1], off offset:2048
	global_load_ushort v22, v[2:3], off offset:2048
	global_load_ushort v23, v[4:5], off offset:2048
	global_load_ushort v24, v[6:7], off offset:2048
	global_load_ushort v25, v[8:9], off offset:2048
	global_load_ushort v26, v[10:11], off offset:2048
	global_load_ushort v27, v[12:13], off offset:2048
	global_load_ushort v28, v[14:15], off offset:2048
	v_add_u32_e32 v0, s1, v29
	v_or_b32_e32 v12, 14, v19
	v_or_b32_e32 v10, 13, v19
	v_add_u32_e32 v8, s1, v30
	v_or_b32_e32 v6, 11, v19
	v_or_b32_e32 v4, 10, v19
	v_or_b32_e32 v2, 9, v19
	v_mad_i64_i32 v[0:1], s[86:87], v0, s49, v[164:165]
	v_or_b32_e32 v14, 15, v19
	v_mad_i64_i32 v[8:9], s[86:87], v8, s49, v[164:165]
	v_mad_i64_i32 v[10:11], s[86:87], v10, s49, v[164:165]
	v_mad_i64_i32 v[12:13], s[86:87], v12, s49, v[164:165]
	v_mad_i64_i32 v[2:3], s[86:87], v2, s49, v[164:165]
	v_mad_i64_i32 v[4:5], s[86:87], v4, s49, v[164:165]
	v_mad_i64_i32 v[6:7], s[86:87], v6, s49, v[164:165]
	v_lshl_add_u64 v[0:1], v[0:1], 0, s[6:7]
	v_mad_i64_i32 v[14:15], s[86:87], v14, s49, v[164:165]
	v_lshl_add_u64 v[8:9], v[8:9], 0, s[6:7]
	v_lshl_add_u64 v[10:11], v[10:11], 0, s[6:7]
	v_lshl_add_u64 v[12:13], v[12:13], 0, s[6:7]
	v_lshl_add_u64 v[2:3], v[2:3], 0, s[6:7]
	v_lshl_add_u64 v[4:5], v[4:5], 0, s[6:7]
	v_lshl_add_u64 v[6:7], v[6:7], 0, s[6:7]
	v_lshl_add_u64 v[0:1], v[0:1], 0, v[166:167]
	v_lshl_add_u64 v[14:15], v[14:15], 0, s[6:7]
	v_lshl_add_u64 v[8:9], v[8:9], 0, v[166:167]
	v_lshl_add_u64 v[10:11], v[10:11], 0, v[166:167]
	v_lshl_add_u64 v[12:13], v[12:13], 0, v[166:167]
	v_or_b32_e32 v40, 16, v17
	v_or_b32_e32 v41, 20, v17
	v_lshl_add_u64 v[2:3], v[2:3], 0, v[166:167]
	v_lshl_add_u64 v[4:5], v[4:5], 0, v[166:167]
	v_lshl_add_u64 v[6:7], v[6:7], 0, v[166:167]
	v_lshl_add_u64 v[14:15], v[14:15], 0, v[166:167]
	global_load_ushort v31, v[0:1], off offset:2048
	global_load_ushort v32, v[2:3], off offset:2048
	global_load_ushort v33, v[4:5], off offset:2048
	global_load_ushort v34, v[6:7], off offset:2048
	global_load_ushort v36, v[8:9], off offset:2048
	global_load_ushort v37, v[10:11], off offset:2048
	global_load_ushort v38, v[12:13], off offset:2048
	global_load_ushort v39, v[14:15], off offset:2048
	v_add_u32_e32 v0, s1, v40
	v_or_b32_e32 v12, 22, v19
	v_or_b32_e32 v10, 21, v19
	v_add_u32_e32 v8, s1, v41
	v_or_b32_e32 v6, 19, v19
	v_or_b32_e32 v4, 18, v19
	v_or_b32_e32 v2, 17, v19
	v_mad_i64_i32 v[0:1], s[86:87], v0, s49, v[164:165]
	v_or_b32_e32 v14, 23, v19
	v_mad_i64_i32 v[8:9], s[86:87], v8, s49, v[164:165]
	v_mad_i64_i32 v[10:11], s[86:87], v10, s49, v[164:165]
	v_mad_i64_i32 v[12:13], s[86:87], v12, s49, v[164:165]
	v_mad_i64_i32 v[2:3], s[86:87], v2, s49, v[164:165]
	v_mad_i64_i32 v[4:5], s[86:87], v4, s49, v[164:165]
	v_mad_i64_i32 v[6:7], s[86:87], v6, s49, v[164:165]
	v_lshl_add_u64 v[0:1], v[0:1], 0, s[6:7]
	v_mad_i64_i32 v[14:15], s[86:87], v14, s49, v[164:165]
	v_lshl_add_u64 v[8:9], v[8:9], 0, s[6:7]
	v_lshl_add_u64 v[10:11], v[10:11], 0, s[6:7]
	v_lshl_add_u64 v[12:13], v[12:13], 0, s[6:7]
	v_lshl_add_u64 v[2:3], v[2:3], 0, s[6:7]
	v_lshl_add_u64 v[4:5], v[4:5], 0, s[6:7]
	v_lshl_add_u64 v[6:7], v[6:7], 0, s[6:7]
	v_lshl_add_u64 v[0:1], v[0:1], 0, v[166:167]
	v_lshl_add_u64 v[14:15], v[14:15], 0, s[6:7]
	v_lshl_add_u64 v[8:9], v[8:9], 0, v[166:167]
	v_lshl_add_u64 v[10:11], v[10:11], 0, v[166:167]
	v_lshl_add_u64 v[12:13], v[12:13], 0, v[166:167]
	v_lshl_add_u64 v[2:3], v[2:3], 0, v[166:167]
	v_lshl_add_u64 v[4:5], v[4:5], 0, v[166:167]
	v_lshl_add_u64 v[6:7], v[6:7], 0, v[166:167]
	v_lshl_add_u64 v[14:15], v[14:15], 0, v[166:167]
	global_load_ushort v42, v[0:1], off offset:2048
	global_load_ushort v43, v[2:3], off offset:2048
	global_load_ushort v44, v[4:5], off offset:2048
	global_load_ushort v45, v[6:7], off offset:2048
	s_nop 0
	global_load_ushort v8, v[8:9], off offset:2048
	s_nop 0
	global_load_ushort v9, v[10:11], off offset:2048
	s_nop 0
	global_load_ushort v10, v[12:13], off offset:2048
	global_load_ushort v11, v[14:15], off offset:2048
	v_or_b32_e32 v12, 24, v17
	v_or_b32_e32 v4, 26, v19
	v_or_b32_e32 v2, 25, v19
	v_add_u32_e32 v0, s1, v12
	v_or_b32_e32 v6, 27, v19
	v_mad_i64_i32 v[0:1], s[86:87], v0, s49, v[164:165]
	v_mad_i64_i32 v[2:3], s[86:87], v2, s49, v[164:165]
	v_mad_i64_i32 v[4:5], s[86:87], v4, s49, v[164:165]
	v_mad_i64_i32 v[6:7], s[86:87], v6, s49, v[164:165]
	v_lshl_add_u64 v[0:1], v[0:1], 0, s[6:7]
	v_lshl_add_u64 v[2:3], v[2:3], 0, s[6:7]
	v_lshl_add_u64 v[4:5], v[4:5], 0, s[6:7]
	v_lshl_add_u64 v[6:7], v[6:7], 0, s[6:7]
	v_lshl_add_u64 v[0:1], v[0:1], 0, v[166:167]
	v_lshl_add_u64 v[2:3], v[2:3], 0, v[166:167]
	v_lshl_add_u64 v[4:5], v[4:5], 0, v[166:167]
	v_or_b32_e32 v47, 28, v17
	v_lshl_add_u64 v[6:7], v[6:7], 0, v[166:167]
	global_load_ushort v13, v[0:1], off offset:2048
	global_load_ushort v14, v[2:3], off offset:2048
	global_load_ushort v15, v[4:5], off offset:2048
	global_load_ushort v46, v[6:7], off offset:2048
	v_or_b32_e32 v4, 30, v19
	v_or_b32_e32 v2, 29, v19
	v_add_u32_e32 v0, s1, v47
	v_or_b32_e32 v6, 31, v19
	v_mad_i64_i32 v[0:1], s[86:87], v0, s49, v[164:165]
	v_mad_i64_i32 v[2:3], s[86:87], v2, s49, v[164:165]
	v_mad_i64_i32 v[4:5], s[86:87], v4, s49, v[164:165]
	v_mad_i64_i32 v[6:7], s[86:87], v6, s49, v[164:165]
	v_lshl_add_u64 v[0:1], v[0:1], 0, s[6:7]
	v_lshl_add_u64 v[2:3], v[2:3], 0, s[6:7]
	v_lshl_add_u64 v[4:5], v[4:5], 0, s[6:7]
	v_lshl_add_u64 v[6:7], v[6:7], 0, s[6:7]
	v_lshl_add_u64 v[0:1], v[0:1], 0, v[166:167]
	v_lshl_add_u64 v[2:3], v[2:3], 0, v[166:167]
	v_lshl_add_u64 v[4:5], v[4:5], 0, v[166:167]
	v_lshl_add_u64 v[6:7], v[6:7], 0, v[166:167]
	global_load_ushort v19, v[0:1], off offset:2048
	s_nop 0
	global_load_ushort v4, v[4:5], off offset:2048
	s_nop 0
	global_load_ushort v5, v[6:7], off offset:2048
	s_nop 0
	global_load_ushort v2, v[2:3], off offset:2048
	v_lshlrev_b32_e32 v3, 1, v17
	s_waitcnt vmcnt(28)
	v_perm_b32 v1, v24, v23, s78
	v_perm_b32 v0, v22, v21, s78
	v_mad_u32_u24 v3, v18, s77, v3
	ds_write_b64 v3, v[0:1] offset:49152
	v_lshlrev_b32_e32 v3, 1, v20
	s_waitcnt vmcnt(24)
	v_perm_b32 v1, v28, v27, s78
	v_perm_b32 v0, v26, v25, s78
	v_mad_u32_u24 v3, v18, s77, v3
	ds_write_b64 v3, v[0:1] offset:49152
	v_lshlrev_b32_e32 v3, 1, v29
	s_waitcnt vmcnt(20)
	v_perm_b32 v1, v34, v33, s78
	v_perm_b32 v0, v32, v31, s78
	v_mad_u32_u24 v3, v18, s77, v3
	ds_write_b64 v3, v[0:1] offset:49152
	v_lshlrev_b32_e32 v3, 1, v30
	s_waitcnt vmcnt(16)
	v_perm_b32 v1, v39, v38, s78
	v_perm_b32 v0, v37, v36, s78
	v_mad_u32_u24 v3, v18, s77, v3
	ds_write_b64 v3, v[0:1] offset:49152
	v_lshlrev_b32_e32 v3, 1, v40
	v_mad_u32_u24 v3, v18, s77, v3
	s_lshl_b64 s[86:87], s[16:17], 16
	s_add_u32 s86, s46, s86
	s_addc_u32 s87, s47, s87
	s_waitcnt vmcnt(14)
	v_perm_b32 v0, v43, v42, s78
	s_waitcnt vmcnt(12)
	v_perm_b32 v1, v45, v44, s78
	ds_write_b64 v3, v[0:1] offset:49152
	v_lshlrev_b32_e32 v3, 1, v41
	s_waitcnt vmcnt(10)
	v_perm_b32 v0, v9, v8, s78
	s_waitcnt vmcnt(8)
	v_perm_b32 v1, v11, v10, s78
	v_mad_u32_u24 v3, v18, s77, v3
	ds_write_b64 v3, v[0:1] offset:49152
	v_lshlrev_b32_e32 v3, 1, v12
	v_bfi_b32 v12, s21, v35, v180
	v_mad_u32_u24 v3, v18, s77, v3
	v_mad_u64_u32 v[168:169], s[88:89], v12, s77, v[16:17]
	v_mov_b32_e32 v17, v167
	v_mad_u32_u24 v169, v182, s76, v16
	s_waitcnt vmcnt(6)
	v_perm_b32 v0, v14, v13, s78
	v_ashrrev_i32_e32 v13, 31, v12
	s_waitcnt vmcnt(4)
	v_perm_b32 v1, v46, v15, s78
	ds_write_b64 v3, v[0:1] offset:49152
	v_lshl_add_u64 v[14:15], s[86:87], 0, v[16:17]
	v_lshlrev_b64 v[12:13], 8, v[12:13]
	v_lshl_add_u64 v[170:171], v[14:15], 0, v[12:13]
	v_or_b32_e32 v17, 32, v182
	v_mad_u32_u24 v183, v17, s76, v16
	v_mov_b32_e32 v12, v205
	s_add_u32 s86, s44, s6
	s_addc_u32 s87, s45, 0
	v_mov_b64_e32 v[172:173], s[86:87]
	s_waitcnt vmcnt(1)
	v_perm_b32 v1, v5, v4, s78
	s_waitcnt vmcnt(0)
	v_perm_b32 v0, v2, v19, s78
	v_lshlrev_b32_e32 v2, 1, v47
	v_mad_u32_u24 v2, v18, s77, v2
	ds_write_b64 v2, v[0:1] offset:49152
	s_waitcnt lgkmcnt(0)
	s_barrier
	ds_read_b128 v[0:3], v168 offset:49152
	ds_read_b128 v[148:151], v168 offset:49184
	ds_read_b128 v[8:11], v200 offset:39936
	ds_read_b128 v[160:163], v200 offset:39968
	ds_read_b128 v[4:7], v200 offset:44544
	ds_read_b128 v[156:159], v200 offset:44576
	ds_read_b128 v[140:143], v168 offset:49216
	ds_read_b128 v[120:123], v168 offset:49248
	ds_read_b128 v[152:155], v200 offset:40000
	ds_read_b128 v[136:139], v200 offset:40032
	ds_read_b128 v[144:147], v200 offset:44608
	ds_read_b128 v[128:131], v200 offset:44640
	global_load_dwordx4 v[116:119], v[170:171], off
	global_load_dwordx4 v[104:107], v[170:171], off offset:32
	ds_read_b128 v[132:135], v169 offset:5120
	ds_read_b128 v[112:115], v169 offset:5152
	ds_read_b128 v[124:127], v183 offset:5120
	ds_read_b128 v[108:111], v183 offset:5152
	global_load_dwordx4 v[92:95], v[170:171], off offset:64
	global_load_dwordx4 v[76:79], v[170:171], off offset:96
	ds_read_b128 v[100:103], v169 offset:5184
	ds_read_b128 v[88:91], v169 offset:5216
	ds_read_b128 v[96:99], v183 offset:5184
	ds_read_b128 v[84:87], v183 offset:5216
	global_load_dwordx4 v[68:71], v[170:171], off offset:128
	global_load_dwordx4 v[52:55], v[170:171], off offset:160
	ds_read_b128 v[80:83], v169 offset:5248
	ds_read_b128 v[64:67], v169 offset:5280
	ds_read_b128 v[72:75], v183 offset:5248
	ds_read_b128 v[60:63], v183 offset:5280
	global_load_dwordx4 v[44:47], v[170:171], off offset:192
	global_load_dwordx4 v[32:35], v[170:171], off offset:224
	ds_read_b128 v[56:59], v169 offset:5312
	ds_read_b128 v[40:43], v169 offset:5344
	ds_read_b128 v[48:51], v183 offset:5312
	ds_read_b128 v[36:39], v183 offset:5344
	s_waitcnt lgkmcnt(0)
	s_barrier
	s_nop 0
	v_ashrrev_i32_e32 v13, 2, v12
	v_and_b32_e32 v201, 0xffffffe0, v13
	v_add_u32_e32 v203, s1, v201
	v_and_b32_e32 v202, 0x7f, v12
	v_or_b32_e32 v14, 1, v203
	v_or_b32_e32 v18, 3, v203
	v_or_b32_e32 v16, 2, v203
	v_mad_i64_i32 v[12:13], s[86:87], v203, s49, v[172:173]
	v_mad_i64_i32 v[14:15], s[86:87], v14, s49, v[172:173]
	v_lshlrev_b32_e32 v166, 1, v202
	v_or_b32_e32 v204, 4, v201
	v_mad_i64_i32 v[16:17], s[86:87], v16, s49, v[172:173]
	v_mad_i64_i32 v[18:19], s[86:87], v18, s49, v[172:173]
	v_lshl_add_u64 v[184:185], v[12:13], 0, v[166:167]
	v_lshl_add_u64 v[186:187], v[14:15], 0, v[166:167]
	v_or_b32_e32 v192, 7, v203
	v_or_b32_e32 v193, 6, v203
	v_or_b32_e32 v14, 5, v203
	v_add_u32_e32 v12, s1, v204
	v_lshl_add_u64 v[188:189], v[16:17], 0, v[166:167]
	v_lshl_add_u64 v[190:191], v[18:19], 0, v[166:167]
	v_mad_i64_i32 v[12:13], s[86:87], v12, s49, v[172:173]
	v_mad_i64_i32 v[14:15], s[86:87], v14, s49, v[172:173]
	v_mfma_f32_32x32x16_bf16 v[16:31], v[8:11], v[0:3], 0
	v_mad_i64_i32 v[8:9], s[86:87], v193, s49, v[172:173]
	v_mad_i64_i32 v[10:11], s[86:87], v192, s49, v[172:173]
	v_lshl_add_u64 v[192:193], v[12:13], 0, v[166:167]
	v_lshl_add_u64 v[194:195], v[14:15], 0, v[166:167]
	v_lshl_add_u64 v[196:197], v[8:9], 0, v[166:167]
	v_lshl_add_u64 v[198:199], v[10:11], 0, v[166:167]
	v_mfma_f32_32x32x16_bf16 v[0:15], v[4:7], v[0:3], 0
	global_load_ushort v206, v[184:185], off offset:2304
	s_nop 0
	global_load_ushort v186, v[186:187], off offset:2304
	s_nop 0
	global_load_ushort v187, v[188:189], off offset:2304
	s_nop 0
	global_load_ushort v188, v[190:191], off offset:2304
	global_load_ushort v189, v[192:193], off offset:2304
	s_nop 0
	global_load_ushort v190, v[194:195], off offset:2304
	global_load_ushort v191, v[196:197], off offset:2304
	global_load_ushort v192, v[198:199], off offset:2304
	v_or_b32_e32 v193, 8, v201
	v_or_b32_e32 v185, 9, v203
	v_or_b32_e32 v194, 11, v203
	v_or_b32_e32 v184, 10, v203
	v_mfma_f32_32x32x16_bf16 v[16:31], v[160:163], v[148:151], v[16:31]
	v_add_u32_e32 v160, s1, v193
	v_mad_i64_i32 v[160:161], s[86:87], v160, s49, v[172:173]
	v_mad_i64_i32 v[162:163], s[86:87], v185, s49, v[172:173]
	v_mad_i64_i32 v[184:185], s[86:87], v184, s49, v[172:173]
	v_mfma_f32_32x32x16_bf16 v[0:15], v[156:159], v[148:151], v[0:15]
	v_lshl_add_u64 v[150:151], v[160:161], 0, v[166:167]
	v_or_b32_e32 v160, 12, v201
	v_lshl_add_u64 v[156:157], v[162:163], 0, v[166:167]
	v_or_b32_e32 v161, 15, v203
	v_or_b32_e32 v162, 14, v203
	v_mad_i64_i32 v[148:149], s[86:87], v194, s49, v[172:173]
	v_mfma_f32_32x32x16_bf16 v[16:31], v[152:155], v[140:143], v[16:31]
	v_add_u32_e32 v152, s1, v160
	v_or_b32_e32 v154, 13, v203
	v_mad_i64_i32 v[152:153], s[86:87], v152, s49, v[172:173]
	v_mad_i64_i32 v[154:155], s[86:87], v154, s49, v[172:173]
	v_lshl_add_u64 v[158:159], v[184:185], 0, v[166:167]
	v_mfma_f32_32x32x16_bf16 v[0:15], v[144:147], v[140:143], v[0:15]
	v_mad_i64_i32 v[140:141], s[86:87], v162, s49, v[172:173]
	v_mad_i64_i32 v[142:143], s[86:87], v161, s49, v[172:173]
	v_lshl_add_u64 v[144:145], v[152:153], 0, v[166:167]
	v_lshl_add_u64 v[140:141], v[140:141], 0, v[166:167]
	v_lshl_add_u64 v[142:143], v[142:143], 0, v[166:167]
	v_mfma_f32_32x32x16_bf16 v[16:31], v[136:139], v[120:123], v[16:31]
	v_lshl_add_u64 v[148:149], v[148:149], 0, v[166:167]
	v_lshl_add_u64 v[146:147], v[154:155], 0, v[166:167]
	global_load_ushort v136, v[150:151], off offset:2304
	global_load_ushort v137, v[156:157], off offset:2304
	global_load_ushort v138, v[158:159], off offset:2304
	global_load_ushort v139, v[148:149], off offset:2304
	s_nop 0
	global_load_ushort v144, v[144:145], off offset:2304
	s_nop 0
	global_load_ushort v145, v[146:147], off offset:2304
	s_nop 0
	global_load_ushort v140, v[140:141], off offset:2304
	s_nop 0
	global_load_ushort v141, v[142:143], off offset:2304
	v_or_b32_e32 v142, 16, v201
	v_or_b32_e32 v143, 19, v203
	v_or_b32_e32 v146, 18, v203
	v_or_b32_e32 v147, 17, v203
	v_mfma_f32_32x32x16_bf16 v[0:15], v[128:131], v[120:123], v[0:15]
	v_add_u32_e32 v120, s1, v142
	v_mad_i64_i32 v[120:121], s[86:87], v120, s49, v[172:173]
	v_mad_i64_i32 v[122:123], s[86:87], v147, s49, v[172:173]
	v_mad_i64_i32 v[128:129], s[86:87], v146, s49, v[172:173]
	s_waitcnt vmcnt(23)
	v_mfma_f32_32x32x16_bf16 v[16:31], v[132:135], v[116:119], v[16:31]
	v_or_b32_e32 v132, 20, v201
	v_or_b32_e32 v133, 23, v203
	v_mad_i64_i32 v[130:131], s[86:87], v143, s49, v[172:173]
	v_lshl_add_u64 v[120:121], v[120:121], 0, v[166:167]
	v_lshl_add_u64 v[122:123], v[122:123], 0, v[166:167]
	v_lshl_add_u64 v[128:129], v[128:129], 0, v[166:167]
	v_mfma_f32_32x32x16_bf16 v[0:15], v[124:127], v[116:119], v[0:15]
	v_or_b32_e32 v124, 22, v203
	v_or_b32_e32 v118, 21, v203
	v_add_u32_e32 v116, s1, v132
	v_mad_i64_i32 v[116:117], s[86:87], v116, s49, v[172:173]
	v_mad_i64_i32 v[118:119], s[86:87], v118, s49, v[172:173]
	s_waitcnt vmcnt(22)
	v_mfma_f32_32x32x16_bf16 v[16:31], v[112:115], v[104:107], v[16:31]
	v_mad_i64_i32 v[112:113], s[86:87], v124, s49, v[172:173]
	v_mad_i64_i32 v[114:115], s[86:87], v133, s49, v[172:173]
	v_lshl_add_u64 v[112:113], v[112:113], 0, v[166:167]
	v_lshl_add_u64 v[130:131], v[130:131], 0, v[166:167]
	v_lshl_add_u64 v[116:117], v[116:117], 0, v[166:167]
	v_mfma_f32_32x32x16_bf16 v[0:15], v[108:111], v[104:107], v[0:15]
	v_lshl_add_u64 v[118:119], v[118:119], 0, v[166:167]
	v_lshl_add_u64 v[114:115], v[114:115], 0, v[166:167]
	global_load_ushort v104, v[120:121], off offset:2304
	global_load_ushort v105, v[122:123], off offset:2304
	global_load_ushort v106, v[128:129], off offset:2304
	global_load_ushort v107, v[130:131], off offset:2304
	global_load_ushort v108, v[116:117], off offset:2304
	global_load_ushort v109, v[118:119], off offset:2304
	global_load_ushort v110, v[112:113], off offset:2304
	global_load_ushort v111, v[114:115], off offset:2304
	v_or_b32_e32 v112, 24, v201
	v_or_b32_e32 v113, 27, v203
	v_or_b32_e32 v114, 26, v203
	s_waitcnt vmcnt(29)
	v_mfma_f32_32x32x16_bf16 v[16:31], v[100:103], v[92:95], v[16:31]
	v_add_u32_e32 v100, s1, v112
	v_or_b32_e32 v102, 25, v203
	v_mad_i64_i32 v[100:101], s[86:87], v100, s49, v[172:173]
	v_mad_i64_i32 v[102:103], s[86:87], v102, s49, v[172:173]
	v_mfma_f32_32x32x16_bf16 v[0:15], v[96:99], v[92:95], v[0:15]
	v_mad_i64_i32 v[92:93], s[86:87], v114, s49, v[172:173]
	v_mad_i64_i32 v[94:95], s[86:87], v113, s49, v[172:173]
	v_lshl_add_u64 v[96:97], v[100:101], 0, v[166:167]
	v_lshl_add_u64 v[92:93], v[92:93], 0, v[166:167]
	v_lshl_add_u64 v[98:99], v[102:103], 0, v[166:167]
	s_waitcnt vmcnt(28)
	v_mfma_f32_32x32x16_bf16 v[16:31], v[88:91], v[76:79], v[16:31]
	v_lshl_add_u64 v[88:89], v[94:95], 0, v[166:167]
	global_load_ushort v90, v[96:97], off offset:2304
	global_load_ushort v91, v[98:99], off offset:2304
	s_nop 0
	global_load_ushort v92, v[92:93], off offset:2304
	s_nop 0
	global_load_ushort v88, v[88:89], off offset:2304
	v_or_b32_e32 v89, 28, v201
	v_or_b32_e32 v93, 31, v203
	v_mfma_f32_32x32x16_bf16 v[0:15], v[84:87], v[76:79], v[0:15]
	v_add_u32_e32 v76, s1, v89
	v_or_b32_e32 v84, 30, v203
	v_or_b32_e32 v78, 29, v203
	v_mad_i64_i32 v[76:77], s[86:87], v76, s49, v[172:173]
	v_mad_i64_i32 v[78:79], s[86:87], v78, s49, v[172:173]
	s_waitcnt vmcnt(31)
	v_mfma_f32_32x32x16_bf16 v[16:31], v[80:83], v[68:71], v[16:31]
	v_mad_i64_i32 v[80:81], s[86:87], v84, s49, v[172:173]
	v_mad_i64_i32 v[82:83], s[86:87], v93, s49, v[172:173]
	v_lshl_add_u64 v[76:77], v[76:77], 0, v[166:167]
	v_lshl_add_u64 v[78:79], v[78:79], 0, v[166:167]
	v_lshl_add_u64 v[80:81], v[80:81], 0, v[166:167]
	v_lshl_add_u64 v[82:83], v[82:83], 0, v[166:167]
	v_mfma_f32_32x32x16_bf16 v[0:15], v[72:75], v[68:71], v[0:15]
	global_load_ushort v70, v[76:77], off offset:2304
	global_load_ushort v71, v[80:81], off offset:2304
	global_load_ushort v72, v[82:83], off offset:2304
	global_load_ushort v73, v[78:79], off offset:2304
	v_lshlrev_b32_e32 v74, 1, v201
	s_waitcnt vmcnt(28)
	v_perm_b32 v69, v188, v187, s78
	v_perm_b32 v68, v186, v206, s78
	v_mad_u32_u24 v74, v202, s77, v74
	ds_write_b64 v74, v[68:69] offset:49152
	v_mfma_f32_32x32x16_bf16 v[16:31], v[64:67], v[52:55], v[16:31]
	v_lshlrev_b32_e32 v66, 1, v204
	s_waitcnt vmcnt(24)
	v_perm_b32 v65, v192, v191, s78
	v_perm_b32 v64, v190, v189, s78
	v_mad_u32_u24 v66, v202, s77, v66
	ds_write_b64 v66, v[64:65] offset:49152
	s_waitcnt vmcnt(20)
	v_perm_b32 v65, v139, v138, s78
	v_perm_b32 v64, v137, v136, s78
	v_mfma_f32_32x32x16_bf16 v[0:15], v[60:63], v[52:55], v[0:15]
	v_lshlrev_b32_e32 v52, 1, v193
	v_mad_u32_u24 v52, v202, s77, v52
	v_lshlrev_b32_e32 v54, 1, v160
	ds_write_b64 v52, v[64:65] offset:49152
	s_waitcnt vmcnt(16)
	v_perm_b32 v53, v141, v140, s78
	v_perm_b32 v52, v145, v144, s78
	v_mad_u32_u24 v54, v202, s77, v54
	v_mfma_f32_32x32x16_bf16 v[16:31], v[56:59], v[44:47], v[16:31]
	ds_write_b64 v54, v[52:53] offset:49152
	v_lshlrev_b32_e32 v54, 1, v142
	v_mad_u32_u24 v54, v202, s77, v54
	s_waitcnt vmcnt(14)
	v_perm_b32 v52, v105, v104, s78
	s_waitcnt vmcnt(12)
	v_perm_b32 v53, v107, v106, s78
	ds_write_b64 v54, v[52:53] offset:49152
	v_mfma_f32_32x32x16_bf16 v[0:15], v[48:51], v[44:47], v[0:15]
	v_lshlrev_b32_e32 v44, 1, v132
	s_waitcnt vmcnt(8)
	v_perm_b32 v53, v111, v110, s78
	v_perm_b32 v52, v109, v108, s78
	v_mad_u32_u24 v44, v202, s77, v44
	v_lshlrev_b32_e32 v46, 1, v112
	ds_write_b64 v44, v[52:53] offset:49152
	s_waitcnt vmcnt(6)
	v_perm_b32 v44, v91, v90, s78
	v_mfma_f32_32x32x16_bf16 v[16:31], v[40:43], v[32:35], v[16:31]
	s_waitcnt vmcnt(4)
	v_perm_b32 v45, v88, v92, s78
	v_mad_u32_u24 v40, v202, s77, v46
	v_lshlrev_b32_e32 v42, 1, v89
	ds_write_b64 v40, v[44:45] offset:49152
	v_mad_u32_u24 v42, v202, s77, v42
	v_lshl_add_u64 v[88:89], v[170:171], 0, s[12:13]
	s_nop 4
	v_cvt_pk_bf16_f32 v16, v16, s0
	v_mfma_f32_32x32x16_bf16 v[0:15], v[36:39], v[32:35], v[0:15]
	s_waitcnt vmcnt(1)
	v_perm_b32 v41, v72, v71, s78
	s_waitcnt vmcnt(0)
	v_perm_b32 v40, v73, v70, s78
	ds_write_b64 v42, v[40:41] offset:49152
	s_waitcnt lgkmcnt(0)
	s_barrier
	ds_read_b128 v[32:35], v200 offset:39936
	ds_read_b128 v[36:39], v168 offset:49152
	ds_read_b128 v[64:67], v168 offset:49184
	ds_read_b128 v[68:71], v200 offset:39968
	s_waitcnt lgkmcnt(2)
	v_mfma_f32_32x32x16_bf16 v[48:63], v[32:35], v[36:39], 0
	ds_read_b128 v[32:35], v200 offset:44544
	ds_read_b128 v[72:75], v200 offset:44576
	v_cvt_pk_bf16_f32 v0, v0, s0
	s_waitcnt lgkmcnt(1)
	v_mfma_f32_32x32x16_bf16 v[32:47], v[32:35], v[36:39], 0
	v_mfma_f32_32x32x16_bf16 v[48:63], v[68:71], v[64:67], v[48:63]
	s_waitcnt lgkmcnt(0)
	v_mfma_f32_32x32x16_bf16 v[32:47], v[72:75], v[64:67], v[32:47]
	ds_read_b128 v[64:67], v200 offset:40000
	ds_read_b128 v[68:71], v168 offset:49216
	ds_read_b128 v[72:75], v168 offset:49248
	ds_read_b128 v[76:79], v200 offset:40032
	s_waitcnt lgkmcnt(2)
	v_mfma_f32_32x32x16_bf16 v[48:63], v[64:67], v[68:71], v[48:63]
	ds_read_b128 v[64:67], v200 offset:44608
	ds_read_b128 v[80:83], v200 offset:44640
	s_waitcnt lgkmcnt(1)
	v_mfma_f32_32x32x16_bf16 v[32:47], v[64:67], v[68:71], v[32:47]
	v_add_co_u32_e32 v64, vcc, s79, v170
	ds_read_b128 v[68:71], v169 offset:5120
	s_nop 0
	v_addc_co_u32_e32 v65, vcc, 0, v171, vcc
	global_load_dwordx4 v[64:67], v[64:65], off
	v_mfma_f32_32x32x16_bf16 v[48:63], v[76:79], v[72:75], v[48:63]
	ds_read_b128 v[76:79], v169 offset:5152
	s_waitcnt lgkmcnt(2)
	v_mfma_f32_32x32x16_bf16 v[32:47], v[80:83], v[72:75], v[32:47]
	global_load_dwordx4 v[72:75], v[88:89], off offset:32
	global_load_dwordx4 v[80:83], v[88:89], off offset:224
	s_waitcnt vmcnt(2) lgkmcnt(1)
	v_mfma_f32_32x32x16_bf16 v[48:63], v[68:71], v[64:67], v[48:63]
	ds_read_b128 v[68:71], v183 offset:5120
	ds_read_b128 v[84:87], v183 offset:5152
	s_waitcnt lgkmcnt(1)
	v_mfma_f32_32x32x16_bf16 v[32:47], v[68:71], v[64:67], v[32:47]
	global_load_dwordx4 v[64:67], v[88:89], off offset:64
	ds_read_b128 v[68:71], v169 offset:5184
	s_waitcnt vmcnt(2)
	v_mfma_f32_32x32x16_bf16 v[48:63], v[76:79], v[72:75], v[48:63]
	ds_read_b128 v[76:79], v169 offset:5216
	s_waitcnt lgkmcnt(2)
	v_mfma_f32_32x32x16_bf16 v[32:47], v[84:87], v[72:75], v[32:47]
	global_load_dwordx4 v[72:75], v[88:89], off offset:96
	s_waitcnt vmcnt(1) lgkmcnt(1)
	v_mfma_f32_32x32x16_bf16 v[48:63], v[68:71], v[64:67], v[48:63]
	ds_read_b128 v[68:71], v183 offset:5184
	ds_read_b128 v[84:87], v183 offset:5216
	s_waitcnt lgkmcnt(1)
	v_mfma_f32_32x32x16_bf16 v[32:47], v[68:71], v[64:67], v[32:47]
	global_load_dwordx4 v[64:67], v[88:89], off offset:128
	ds_read_b128 v[68:71], v169 offset:5248
	s_waitcnt vmcnt(1)
	v_mfma_f32_32x32x16_bf16 v[48:63], v[76:79], v[72:75], v[48:63]
	ds_read_b128 v[76:79], v169 offset:5280
	s_waitcnt lgkmcnt(2)
	v_mfma_f32_32x32x16_bf16 v[32:47], v[84:87], v[72:75], v[32:47]
	global_load_dwordx4 v[72:75], v[88:89], off offset:160
	s_waitcnt vmcnt(1) lgkmcnt(1)
	v_mfma_f32_32x32x16_bf16 v[48:63], v[68:71], v[64:67], v[48:63]
	ds_read_b128 v[68:71], v183 offset:5248
	ds_read_b128 v[84:87], v183 offset:5280
	s_waitcnt lgkmcnt(1)
	v_mfma_f32_32x32x16_bf16 v[32:47], v[68:71], v[64:67], v[32:47]
	global_load_dwordx4 v[64:67], v[88:89], off offset:192
	s_waitcnt vmcnt(1)
	v_mfma_f32_32x32x16_bf16 v[48:63], v[76:79], v[72:75], v[48:63]
	s_waitcnt lgkmcnt(0)
	v_mfma_f32_32x32x16_bf16 v[32:47], v[84:87], v[72:75], v[32:47]
	ds_read_b128 v[68:71], v169 offset:5312
	ds_read_b128 v[72:75], v169 offset:5344
	v_add_u32_e32 v84, s1, v179
	v_ashrrev_i32_e32 v85, 31, v84
	s_waitcnt vmcnt(0) lgkmcnt(1)
	v_mfma_f32_32x32x16_bf16 v[48:63], v[68:71], v[64:67], v[48:63]
	ds_read_b128 v[68:71], v183 offset:5312
	ds_read_b128 v[76:79], v183 offset:5344
	s_waitcnt lgkmcnt(0)
	s_barrier
	v_mfma_f32_32x32x16_bf16 v[32:47], v[68:71], v[64:67], v[32:47]
	v_lshlrev_b32_e32 v64, 1, v182
	v_and_or_b32 v64, v180, s20, v64
	v_mad_u32_u24 v64, v181, s80, v64
	ds_write_b16 v64, v0 offset:22016
	v_cvt_pk_bf16_f32 v0, v1, s0
	ds_write_b16 v64, v0 offset:22544
	v_cvt_pk_bf16_f32 v0, v2, s0
	ds_write_b16 v64, v0 offset:23072
	v_cvt_pk_bf16_f32 v0, v3, s0
	ds_write_b16 v64, v0 offset:23600
	v_cvt_pk_bf16_f32 v0, v4, s0
	ds_write_b16 v64, v0 offset:26240
	v_cvt_pk_bf16_f32 v0, v5, s0
	ds_write_b16 v64, v0 offset:26768
	v_cvt_pk_bf16_f32 v0, v6, s0
	ds_write_b16 v64, v0 offset:27296
	v_cvt_pk_bf16_f32 v0, v7, s0
	v_mfma_f32_32x32x16_bf16 v[48:63], v[72:75], v[80:83], v[48:63]
	ds_write_b16 v64, v0 offset:27824
	v_cvt_pk_bf16_f32 v0, v8, s0
	ds_write_b16 v64, v0 offset:30464
	v_cvt_pk_bf16_f32 v0, v9, s0
	ds_write_b16 v64, v0 offset:30992
	v_cvt_pk_bf16_f32 v0, v10, s0
	ds_write_b16 v64, v0 offset:31520
	v_cvt_pk_bf16_f32 v0, v11, s0
	ds_write_b16 v64, v0 offset:32048
	v_cvt_pk_bf16_f32 v0, v12, s0
	ds_write_b16 v64, v0 offset:34688
	v_cvt_pk_bf16_f32 v0, v13, s0
	ds_write_b16 v64, v0 offset:35216
	v_cvt_pk_bf16_f32 v0, v14, s0
	ds_write_b16 v64, v0 offset:35744
	v_cvt_pk_bf16_f32 v0, v15, s0
	ds_write_b16 v64, v0 offset:36272
	v_cvt_pk_bf16_f32 v0, v48, s0
	ds_write_b16 v64, v0 offset:5376
	v_cvt_pk_bf16_f32 v0, v49, s0
	ds_write_b16 v64, v0 offset:5904
	v_cvt_pk_bf16_f32 v0, v50, s0
	ds_write_b16 v64, v0 offset:6432
	v_cvt_pk_bf16_f32 v0, v51, s0
	ds_write_b16 v64, v0 offset:6960
	v_cvt_pk_bf16_f32 v0, v52, s0
	ds_write_b16 v64, v0 offset:9600
	v_cvt_pk_bf16_f32 v0, v53, s0
	ds_write_b16 v64, v0 offset:10128
	v_cvt_pk_bf16_f32 v0, v54, s0
	ds_write_b16 v64, v0 offset:10656
	v_cvt_pk_bf16_f32 v0, v55, s0
	v_mfma_f32_32x32x16_bf16 v[32:47], v[76:79], v[80:83], v[32:47]
	ds_write_b16 v64, v0 offset:11184
	v_cvt_pk_bf16_f32 v0, v56, s0
	ds_write_b16 v64, v0 offset:13824
	v_cvt_pk_bf16_f32 v0, v57, s0
	ds_write_b16 v64, v0 offset:14352
	v_cvt_pk_bf16_f32 v0, v58, s0
	ds_write_b16 v64, v0 offset:14880
	v_cvt_pk_bf16_f32 v0, v59, s0
	ds_write_b16 v64, v0 offset:15408
	v_cvt_pk_bf16_f32 v0, v60, s0
	ds_write_b16 v64, v0 offset:18048
	v_cvt_pk_bf16_f32 v0, v61, s0
	ds_write_b16 v64, v0 offset:18576
	v_cvt_pk_bf16_f32 v0, v62, s0
	ds_write_b16 v64, v0 offset:19104
	v_cvt_pk_bf16_f32 v0, v63, s0
	ds_write_b16 v64, v0 offset:19632
	v_cvt_pk_bf16_f32 v0, v32, s0
	ds_write_b16 v64, v0 offset:22272
	v_cvt_pk_bf16_f32 v0, v33, s0
	ds_write_b16 v64, v0 offset:22800
	v_cvt_pk_bf16_f32 v0, v34, s0
	ds_write_b16 v64, v0 offset:23328
	v_cvt_pk_bf16_f32 v0, v35, s0
	ds_write_b16 v64, v0 offset:23856
	v_cvt_pk_bf16_f32 v0, v36, s0
	ds_write_b16 v64, v16 offset:5120
	v_cvt_pk_bf16_f32 v16, v17, s0
	ds_write_b16 v64, v0 offset:26496
	v_cvt_pk_bf16_f32 v0, v37, s0
	ds_write_b16 v64, v16 offset:5648
	v_cvt_pk_bf16_f32 v16, v18, s0
	ds_write_b16 v64, v0 offset:27024
	v_cvt_pk_bf16_f32 v0, v38, s0
	ds_write_b16 v64, v16 offset:6176
	v_cvt_pk_bf16_f32 v16, v19, s0
	ds_write_b16 v64, v0 offset:27552
	v_cvt_pk_bf16_f32 v0, v39, s0
	ds_write_b16 v64, v16 offset:6704
	v_cvt_pk_bf16_f32 v16, v20, s0
	ds_write_b16 v64, v0 offset:28080
	v_cvt_pk_bf16_f32 v0, v40, s0
	ds_write_b16 v64, v16 offset:9344
	v_cvt_pk_bf16_f32 v16, v21, s0
	ds_write_b16 v64, v0 offset:30720
	v_cvt_pk_bf16_f32 v0, v41, s0
	ds_write_b16 v64, v16 offset:9872
	v_cvt_pk_bf16_f32 v16, v22, s0
	ds_write_b16 v64, v0 offset:31248
	v_cvt_pk_bf16_f32 v0, v42, s0
	ds_write_b16 v64, v16 offset:10400
	v_cvt_pk_bf16_f32 v16, v23, s0
	ds_write_b16 v64, v0 offset:31776
	v_cvt_pk_bf16_f32 v0, v43, s0
	ds_write_b16 v64, v16 offset:10928
	v_cvt_pk_bf16_f32 v16, v24, s0
	ds_write_b16 v64, v0 offset:32304
	v_cvt_pk_bf16_f32 v0, v44, s0
	ds_write_b16 v64, v16 offset:13568
	v_cvt_pk_bf16_f32 v16, v25, s0
	ds_write_b16 v64, v0 offset:34944
	v_cvt_pk_bf16_f32 v0, v45, s0
	ds_write_b16 v64, v16 offset:14096
	v_cvt_pk_bf16_f32 v16, v26, s0
	ds_write_b16 v64, v0 offset:35472
	v_cvt_pk_bf16_f32 v0, v46, s0
	ds_write_b16 v64, v16 offset:14624
	v_cvt_pk_bf16_f32 v16, v27, s0
	ds_write_b16 v64, v0 offset:36000
	v_cvt_pk_bf16_f32 v0, v47, s0
	ds_write_b16 v64, v16 offset:15152
	v_cvt_pk_bf16_f32 v16, v28, s0
	ds_write_b16 v64, v0 offset:36528
	v_lshlrev_b32_e32 v0, 6, v180
	ds_write_b16 v64, v16 offset:17792
	v_cvt_pk_bf16_f32 v16, v29, s0
	v_and_b32_e32 v86, 0xc0, v0
	ds_write_b16 v64, v16 offset:18320
	v_cvt_pk_bf16_f32 v16, v30, s0
	v_lshlrev_b32_e32 v166, 1, v86
	ds_write_b16 v64, v16 offset:18848
	v_cvt_pk_bf16_f32 v16, v31, s0
	v_mad_u64_u32 v[20:21], s[86:87], v179, s81, v[166:167]
	ds_write_b16 v64, v16 offset:19376
	s_waitcnt lgkmcnt(0)
	s_barrier
	ds_read_b128 v[0:3], v20 offset:5120
	ds_read_b128 v[4:7], v20 offset:5136
	ds_read_b128 v[8:11], v20 offset:5152
	ds_read_b128 v[16:19], v20 offset:5168
	v_lshlrev_b32_e32 v102, 2, v86
	s_waitcnt lgkmcnt(3)
	v_lshlrev_b32_e32 v80, 16, v0
	v_and_b32_e32 v81, 0xffff0000, v0
	v_lshlrev_b32_e32 v78, 16, v1
	v_and_b32_e32 v79, 0xffff0000, v1
	v_mad_i64_i32 v[0:1], s[86:87], v84, s49, v[164:165]
	v_lshl_add_u64 v[0:1], v[0:1], 0, s[6:7]
	v_lshl_add_u64 v[64:65], v[0:1], 0, v[166:167]
	v_add_co_u32_e32 v0, vcc, s82, v64
	s_waitcnt lgkmcnt(2)
	v_lshlrev_b32_e32 v72, 16, v4
	v_addc_co_u32_e32 v1, vcc, 0, v65, vcc
	global_load_dwordx4 v[124:127], v[0:1], off
	global_load_dwordx4 v[128:131], v[0:1], off offset:16
	global_load_dwordx4 v[132:135], v[0:1], off offset:32
	global_load_dwordx4 v[136:139], v[0:1], off offset:48
	global_load_dwordx4 v[140:143], v[0:1], off offset:64
	global_load_dwordx4 v[144:147], v[0:1], off offset:80
	global_load_dwordx4 v[148:151], v[0:1], off offset:96
	global_load_dwordx4 v[152:155], v[0:1], off offset:112
	v_and_b32_e32 v73, 0xffff0000, v4
	v_lshlrev_b32_e32 v70, 16, v5
	v_and_b32_e32 v71, 0xffff0000, v5
	v_lshlrev_b32_e32 v68, 16, v6
	v_and_b32_e32 v69, 0xffff0000, v6
	v_lshlrev_b32_e32 v66, 16, v7
	v_and_b32_e32 v67, 0xffff0000, v7
	v_lshlrev_b32_e32 v76, 16, v2
	v_and_b32_e32 v77, 0xffff0000, v2
	v_lshlrev_b32_e32 v74, 16, v3
	v_and_b32_e32 v75, 0xffff0000, v3
	s_waitcnt lgkmcnt(1)
	v_lshlrev_b32_e32 v54, 16, v8
	v_and_b32_e32 v55, 0xffff0000, v8
	v_lshlrev_b32_e32 v52, 16, v9
	v_and_b32_e32 v53, 0xffff0000, v9
	v_lshlrev_b32_e32 v14, 16, v10
	v_and_b32_e32 v15, 0xffff0000, v10
	v_lshlrev_b32_e32 v12, 16, v11
	v_and_b32_e32 v13, 0xffff0000, v11
	ds_read_b128 v[0:3], v20 offset:5184
	ds_read_b128 v[8:11], v20 offset:5200
	s_waitcnt lgkmcnt(2)
	v_lshlrev_b32_e32 v62, 16, v16
	v_and_b32_e32 v63, 0xffff0000, v16
	v_lshlrev_b32_e32 v60, 16, v17
	s_waitcnt lgkmcnt(1)
	v_and_b32_e32 v48, 0xffff0000, v0
	s_waitcnt lgkmcnt(0)
	v_and_b32_e32 v49, 0xffff0000, v8
	v_lshlrev_b32_e32 v47, 16, v8
	v_lshlrev_b32_e32 v46, 16, v0
	v_lshlrev_b32_e32 v42, 16, v1
	v_and_b32_e32 v44, 0xffff0000, v1
	v_pk_mul_f32 v[0:1], v[48:49], v[48:49]
	v_lshlrev_b32_e32 v43, 16, v9
	v_pk_fma_f32 v[0:1], v[46:47], v[46:47], v[0:1]
	v_and_b32_e32 v45, 0xffff0000, v9
	v_pk_fma_f32 v[0:1], v[42:43], v[42:43], v[0:1]
	v_and_b32_e32 v61, 0xffff0000, v17
	v_lshlrev_b32_e32 v39, 16, v10
	v_lshlrev_b32_e32 v38, 16, v2
	v_and_b32_e32 v41, 0xffff0000, v10
	v_and_b32_e32 v40, 0xffff0000, v2
	v_lshlrev_b32_e32 v35, 16, v11
	v_lshlrev_b32_e32 v34, 16, v3
	v_and_b32_e32 v37, 0xffff0000, v11
	v_and_b32_e32 v36, 0xffff0000, v3
	v_pk_fma_f32 v[16:17], v[44:45], v[44:45], v[0:1]
	ds_read_b128 v[0:3], v20 offset:5216
	ds_read_b128 v[8:11], v20 offset:5232
	v_lshlrev_b32_e32 v58, 16, v18
	v_and_b32_e32 v59, 0xffff0000, v18
	v_lshlrev_b32_e32 v56, 16, v19
	s_waitcnt lgkmcnt(1)
	v_and_b32_e32 v32, 0xffff0000, v0
	s_waitcnt lgkmcnt(0)
	v_and_b32_e32 v33, 0xffff0000, v8
	v_lshlrev_b32_e32 v31, 16, v8
	v_lshlrev_b32_e32 v30, 16, v0
	v_lshlrev_b32_e32 v26, 16, v1
	v_and_b32_e32 v28, 0xffff0000, v1
	v_pk_mul_f32 v[0:1], v[32:33], v[32:33]
	v_lshlrev_b32_e32 v27, 16, v9
	v_pk_fma_f32 v[0:1], v[30:31], v[30:31], v[0:1]
	v_and_b32_e32 v29, 0xffff0000, v9
	v_pk_fma_f32 v[0:1], v[26:27], v[26:27], v[0:1]
	v_lshlrev_b32_e32 v23, 16, v10
	v_lshlrev_b32_e32 v22, 16, v2
	v_pk_fma_f32 v[0:1], v[28:29], v[28:29], v[0:1]
	v_and_b32_e32 v25, 0xffff0000, v10
	v_and_b32_e32 v24, 0xffff0000, v2
	v_pk_fma_f32 v[0:1], v[22:23], v[22:23], v[0:1]
	v_and_b32_e32 v57, 0xffff0000, v19
	v_lshlrev_b32_e32 v19, 16, v11
	v_lshlrev_b32_e32 v18, 16, v3
	v_pk_fma_f32 v[0:1], v[24:25], v[24:25], v[0:1]
	v_and_b32_e32 v21, 0xffff0000, v11
	v_and_b32_e32 v20, 0xffff0000, v3
	v_pk_fma_f32 v[0:1], v[18:19], v[18:19], v[0:1]
	v_cmp_lt_i32_e32 vcc, v175, v176
	v_pk_fma_f32 v[82:83], v[20:21], v[20:21], v[0:1]
	v_pk_fma_f32 v[16:17], v[38:39], v[38:39], v[16:17]
	v_cndmask_b32_e32 v0, v174, v175, vcc
	v_cmp_lt_i32_e32 vcc, v177, v176
	v_lshlrev_b32_e32 v104, 2, v0
	v_pk_fma_f32 v[16:17], v[40:41], v[40:41], v[16:17]
	v_cndmask_b32_e32 v0, v174, v177, vcc
	v_lshlrev_b32_e32 v103, 2, v0
	v_lshlrev_b64 v[0:1], 11, v[84:85]
	v_lshl_add_u64 v[0:1], s[34:35], 0, v[0:1]
	v_pk_fma_f32 v[16:17], v[34:35], v[34:35], v[16:17]
	v_lshl_add_u64 v[64:65], v[64:65], 0, s[14:15]
	v_lshl_add_u64 v[0:1], v[0:1], 0, s[6:7]
	s_waitcnt vmcnt(0)
	v_mov_b32_e32 v4, v124
	v_mov_b32_e32 v5, v125
	v_mov_b32_e32 v6, v126
	v_mov_b32_e32 v7, v127
	v_lshlrev_b32_e32 v86, 16, v6
	v_lshlrev_b32_e32 v92, 16, v4
	v_and_b32_e32 v93, 0xffff0000, v4
	v_and_b32_e32 v87, 0xffff0000, v6
	v_mul_f32_e32 v4, 0xbfb8aa3b, v86
	v_exp_f32_e32 v8, v4
	v_mul_f32_e32 v4, 0xbfb8aa3b, v87
	v_exp_f32_e32 v9, v4
	v_pk_fma_f32 v[50:51], v[36:37], v[36:37], v[16:17]
	v_lshl_add_u64 v[16:17], v[0:1], 0, v[166:167]
	v_pk_add_f32 v[84:85], v[8:9], 1.0 op_sel_hi:[1,0]
	v_lshlrev_b32_e32 v90, 16, v5
	v_div_scale_f32 v88, s[86:87], v85, v85, v87
	v_rcp_f32_e32 v89, v88
	v_and_b32_e32 v91, 0xffff0000, v5
	v_lshlrev_b32_e32 v96, 16, v7
	v_and_b32_e32 v97, 0xffff0000, v7
	v_fma_f32 v94, -v88, v89, 1.0
	v_fmac_f32_e32 v89, v94, v89
	v_div_scale_f32 v94, vcc, v87, v85, v87
	v_mul_f32_e32 v95, v94, v89
	v_fma_f32 v105, -v88, v95, v94
	v_fmac_f32_e32 v95, v105, v89
	v_fma_f32 v88, -v88, v95, v94
	v_div_scale_f32 v94, s[86:87], v84, v84, v86
	v_rcp_f32_e32 v105, v94
	v_div_fmas_f32 v88, v88, v89, v95
	v_div_fixup_f32 v87, v88, v85, v87
	v_mul_f32_e32 v88, 0xbfb8aa3b, v90
	v_mul_f32_e32 v89, 0xbfb8aa3b, v91
	v_fma_f32 v85, -v94, v105, 1.0
	v_exp_f32_e32 v88, v88
	v_exp_f32_e32 v89, v89
	v_fmac_f32_e32 v105, v85, v105
	v_div_scale_f32 v85, vcc, v86, v84, v86
	v_mul_f32_e32 v95, v85, v105
	v_fma_f32 v106, -v94, v95, v85
	v_fmac_f32_e32 v95, v106, v105
	v_pk_add_f32 v[88:89], v[88:89], 1.0 op_sel_hi:[1,0]
	v_fma_f32 v85, -v94, v95, v85
	v_div_scale_f32 v94, s[86:87], v89, v89, v91
	v_rcp_f32_e32 v106, v94
	v_div_fmas_f32 v85, v85, v105, v95
	v_div_fixup_f32 v86, v85, v84, v86
	s_lshl_b32 s0, s0, 10
	v_fma_f32 v84, -v94, v106, 1.0
	v_fmac_f32_e32 v106, v84, v106
	v_div_scale_f32 v84, vcc, v91, v89, v91
	v_mul_f32_e32 v85, v84, v106
	v_fma_f32 v95, -v94, v85, v84
	v_fmac_f32_e32 v85, v95, v106
	v_fma_f32 v84, -v94, v85, v84
	v_div_scale_f32 v94, s[86:87], v88, v88, v90
	v_rcp_f32_e32 v95, v94
	v_div_fmas_f32 v84, v84, v106, v85
	v_div_fixup_f32 v91, v84, v89, v91
	v_mul_f32_e32 v85, 0xbfb8aa3b, v93
	v_fma_f32 v84, -v94, v95, 1.0
	v_fmac_f32_e32 v95, v84, v95
	v_mul_f32_e32 v84, 0xbfb8aa3b, v92
	v_exp_f32_e32 v84, v84
	v_exp_f32_e32 v85, v85
	v_div_scale_f32 v89, vcc, v90, v88, v90
	v_mul_f32_e32 v105, v89, v95
	v_fma_f32 v106, -v94, v105, v89
	v_fmac_f32_e32 v105, v106, v95
	v_pk_add_f32 v[84:85], v[84:85], 1.0 op_sel_hi:[1,0]
	v_fma_f32 v89, -v94, v105, v89
	v_div_scale_f32 v94, s[86:87], v85, v85, v93
	v_rcp_f32_e32 v106, v94
	v_div_fmas_f32 v89, v89, v95, v105
	v_div_fixup_f32 v90, v89, v88, v90
	s_add_u32 s0, s50, s0
	v_fma_f32 v88, -v94, v106, 1.0
	v_fmac_f32_e32 v106, v88, v106
	v_div_scale_f32 v88, vcc, v93, v85, v93
	v_mul_f32_e32 v89, v88, v106
	v_fma_f32 v95, -v94, v89, v88
	v_fmac_f32_e32 v89, v95, v106
	v_fma_f32 v88, -v94, v89, v88
	v_div_scale_f32 v94, s[86:87], v84, v84, v92
	v_rcp_f32_e32 v105, v94
	v_div_fmas_f32 v88, v88, v106, v89
	v_div_fixup_f32 v95, v88, v85, v93
	v_mul_f32_e32 v88, 0xbfb8aa3b, v96
	v_mul_f32_e32 v89, 0xbfb8aa3b, v97
	v_exp_f32_e32 v88, v88
	v_exp_f32_e32 v89, v89
	v_fma_f32 v85, -v94, v105, 1.0
	v_fmac_f32_e32 v105, v85, v105
	v_div_scale_f32 v85, vcc, v92, v84, v92
	v_mul_f32_e32 v93, v85, v105
	v_fma_f32 v106, -v94, v93, v85
	v_pk_add_f32 v[88:89], v[88:89], 1.0 op_sel_hi:[1,0]
	v_fmac_f32_e32 v93, v106, v105
	v_div_scale_f32 v106, s[86:87], v89, v89, v97
	v_rcp_f32_e32 v107, v106
	v_fma_f32 v85, -v94, v93, v85
	v_div_fmas_f32 v85, v85, v105, v93
	v_div_fixup_f32 v94, v85, v84, v92
	v_fma_f32 v84, -v106, v107, 1.0
	v_fmac_f32_e32 v107, v84, v107
	v_div_scale_f32 v84, vcc, v97, v89, v97
	v_mul_f32_e32 v85, v84, v107
	v_fma_f32 v92, -v106, v85, v84
	v_fmac_f32_e32 v85, v92, v107
	v_div_scale_f32 v92, s[86:87], v88, v88, v96
	v_rcp_f32_e32 v93, v92
	v_fma_f32 v84, -v106, v85, v84
	v_div_fmas_f32 v84, v84, v107, v85
	v_div_fixup_f32 v97, v84, v89, v97
	v_fma_f32 v84, -v92, v93, 1.0
	v_fmac_f32_e32 v93, v84, v93
	v_div_scale_f32 v84, vcc, v96, v88, v96
	v_mul_f32_e32 v85, v84, v93
	v_fma_f32 v89, -v92, v85, v84
	v_fmac_f32_e32 v85, v89, v93
	v_fma_f32 v84, -v92, v85, v84
	v_div_fmas_f32 v84, v84, v93, v85
	v_div_fixup_f32 v96, v84, v88, v96
	s_waitcnt vmcnt(0)
	v_mov_b32_e32 v0, v132
	v_mov_b32_e32 v1, v133
	v_mov_b32_e32 v2, v134
	v_mov_b32_e32 v3, v135
	v_mov_b32_e32 v98, v128
	v_mov_b32_e32 v99, v129
	v_mov_b32_e32 v100, v130
	v_mov_b32_e32 v101, v131
	v_lshlrev_b32_e32 v92, 16, v100
	v_and_b32_e32 v88, 0xffff0000, v100
	v_mul_f32_e32 v84, 0xbfb8aa3b, v92
	v_mul_f32_e32 v85, 0xbfb8aa3b, v88
	v_exp_f32_e32 v84, v84
	v_exp_f32_e32 v85, v85
	v_lshlrev_b32_e32 v118, 16, v101
	v_and_b32_e32 v119, 0xffff0000, v101
	v_lshlrev_b32_e32 v105, 16, v99
	v_pk_add_f32 v[84:85], v[84:85], 1.0 op_sel_hi:[1,0]
	v_and_b32_e32 v99, 0xffff0000, v99
	v_div_scale_f32 v89, s[86:87], v85, v85, v88
	v_rcp_f32_e32 v93, v89
	v_lshlrev_b32_e32 v100, 16, v98
	v_and_b32_e32 v98, 0xffff0000, v98
	s_addc_u32 s1, s51, 0
	global_load_dwordx4 v[156:159], v102, s[0:1]
	global_load_dwordx4 v[160:163], v102, s[0:1] offset:16
	global_load_dwordx4 v[168:171], v102, s[0:1] offset:32
	global_load_dwordx4 v[184:187], v102, s[0:1] offset:48
	global_load_dwordx4 v[188:191], v102, s[0:1] offset:64
	global_load_dwordx4 v[192:195], v102, s[0:1] offset:80
	global_load_dwordx4 v[196:199], v102, s[0:1] offset:96
	global_load_dwordx4 v[200:203], v102, s[0:1] offset:112
	global_load_dwordx4 v[208:211], v102, s[0:1] offset:128
	global_load_dwordx4 v[212:215], v102, s[0:1] offset:144
	global_load_dwordx4 v[216:219], v102, s[0:1] offset:160
	global_load_dwordx4 v[220:223], v102, s[0:1] offset:176
	global_load_dwordx4 v[224:227], v102, s[0:1] offset:192
	global_load_dwordx4 v[228:231], v102, s[0:1] offset:208
	global_load_dwordx4 v[232:235], v102, s[0:1] offset:224
	global_load_dwordx4 v[124:127], v102, s[0:1] offset:240
	v_fma_f32 v101, -v89, v93, 1.0
	v_fmac_f32_e32 v93, v101, v93
	v_div_scale_f32 v101, vcc, v88, v85, v88
	v_mul_f32_e32 v106, v101, v93
	v_fma_f32 v107, -v89, v106, v101
	v_fmac_f32_e32 v106, v107, v93
	v_fma_f32 v89, -v89, v106, v101
	v_div_scale_f32 v101, s[86:87], v84, v84, v92
	v_rcp_f32_e32 v107, v101
	v_div_fmas_f32 v89, v89, v93, v106
	v_div_fixup_f32 v85, v89, v85, v88
	v_mul_f32_e32 v89, 0xbfb8aa3b, v99
	v_fma_f32 v88, -v101, v107, 1.0
	v_fmac_f32_e32 v107, v88, v107
	v_mul_f32_e32 v88, 0xbfb8aa3b, v105
	v_exp_f32_e32 v88, v88
	v_exp_f32_e32 v89, v89
	v_div_scale_f32 v93, vcc, v92, v84, v92
	v_mul_f32_e32 v106, v93, v107
	v_fma_f32 v108, -v101, v106, v93
	v_fmac_f32_e32 v106, v108, v107
	v_pk_add_f32 v[88:89], v[88:89], 1.0 op_sel_hi:[1,0]
	v_fma_f32 v93, -v101, v106, v93
	v_div_scale_f32 v101, s[86:87], v89, v89, v99
	v_rcp_f32_e32 v108, v101
	v_div_fmas_f32 v93, v93, v107, v106
	v_div_fixup_f32 v84, v93, v84, v92
	v_fma_f32 v92, -v101, v108, 1.0
	v_fmac_f32_e32 v108, v92, v108
	v_div_scale_f32 v92, vcc, v99, v89, v99
	v_mul_f32_e32 v93, v92, v108
	v_fma_f32 v106, -v101, v93, v92
	v_fmac_f32_e32 v93, v106, v108
	v_fma_f32 v92, -v101, v93, v92
	v_div_scale_f32 v101, s[86:87], v88, v88, v105
	v_rcp_f32_e32 v106, v101
	v_div_fmas_f32 v92, v92, v108, v93
	v_div_fixup_f32 v89, v92, v89, v99
	v_mul_f32_e32 v93, 0xbfb8aa3b, v98
	v_fma_f32 v92, -v101, v106, 1.0
	v_fmac_f32_e32 v106, v92, v106
	v_mul_f32_e32 v92, 0xbfb8aa3b, v100
	v_exp_f32_e32 v92, v92
	v_exp_f32_e32 v93, v93
	v_div_scale_f32 v99, vcc, v105, v88, v105
	v_mul_f32_e32 v107, v99, v106
	v_fma_f32 v108, -v101, v107, v99
	v_fmac_f32_e32 v107, v108, v106
	v_pk_add_f32 v[92:93], v[92:93], 1.0 op_sel_hi:[1,0]
	v_fma_f32 v99, -v101, v107, v99
	v_div_scale_f32 v101, s[86:87], v93, v93, v98
	v_rcp_f32_e32 v108, v101
	v_div_fmas_f32 v99, v99, v106, v107
	v_div_fixup_f32 v88, v99, v88, v105
	v_mov_b32_e32 v116, v81
	v_fma_f32 v99, -v101, v108, 1.0
	v_fmac_f32_e32 v108, v99, v108
	v_div_scale_f32 v99, vcc, v98, v93, v98
	v_mul_f32_e32 v105, v99, v108
	v_fma_f32 v106, -v101, v105, v99
	v_fmac_f32_e32 v105, v106, v108
	v_fma_f32 v99, -v101, v105, v99
	v_div_scale_f32 v101, s[86:87], v92, v92, v100
	v_rcp_f32_e32 v106, v101
	v_div_fmas_f32 v99, v99, v108, v105
	v_div_fixup_f32 v93, v99, v93, v98
	v_mov_b32_e32 v117, v73
	v_fma_f32 v98, -v101, v106, 1.0
	v_fmac_f32_e32 v106, v98, v106
	v_div_scale_f32 v98, vcc, v100, v92, v100
	v_mul_f32_e32 v99, v98, v106
	v_fma_f32 v105, -v101, v99, v98
	v_fmac_f32_e32 v99, v105, v106
	v_mov_b32_e32 v114, v80
	v_mov_b32_e32 v115, v72
	v_pk_mul_f32 v[116:117], v[116:117], v[116:117]
	v_mul_f32_e32 v105, 0xbfb8aa3b, v118
	v_pk_fma_f32 v[114:115], v[114:115], v[114:115], v[116:117]
	v_exp_f32_e32 v116, v105
	v_mul_f32_e32 v105, 0xbfb8aa3b, v119
	v_exp_f32_e32 v117, v105
	v_mov_b32_e32 v110, v78
	v_mov_b32_e32 v111, v70
	v_fma_f32 v98, -v101, v99, v98
	v_mov_b32_e32 v112, v79
	v_mov_b32_e32 v113, v71
	v_pk_fma_f32 v[110:111], v[110:111], v[110:111], v[114:115]
	v_div_fmas_f32 v98, v98, v106, v99
	v_mov_b32_e32 v106, v76
	v_mov_b32_e32 v107, v68
	v_pk_fma_f32 v[110:111], v[112:113], v[112:113], v[110:111]
	v_mov_b32_e32 v108, v77
	v_pk_fma_f32 v[106:107], v[106:107], v[106:107], v[110:111]
	v_pk_add_f32 v[110:111], v[116:117], 1.0 op_sel_hi:[1,0]
	v_mov_b32_e32 v109, v69
	v_div_scale_f32 v105, s[86:87], v111, v111, v119
	v_rcp_f32_e32 v112, v105
	v_div_fixup_f32 v92, v98, v92, v100
	v_mov_b32_e32 v98, v74
	v_mov_b32_e32 v99, v66
	v_pk_fma_f32 v[106:107], v[108:109], v[108:109], v[106:107]
	v_mov_b32_e32 v100, v75
	v_mov_b32_e32 v101, v67
	v_pk_fma_f32 v[98:99], v[98:99], v[98:99], v[106:107]
	v_mov_b32_e32 v120, v55
	v_pk_fma_f32 v[100:101], v[100:101], v[100:101], v[98:99]
	v_fma_f32 v98, -v105, v112, 1.0
	v_fmac_f32_e32 v112, v98, v112
	v_div_scale_f32 v98, vcc, v119, v111, v119
	v_mul_f32_e32 v99, v98, v112
	v_fma_f32 v106, -v105, v99, v98
	v_fmac_f32_e32 v99, v106, v112
	v_fma_f32 v98, -v105, v99, v98
	v_div_scale_f32 v105, s[86:87], v110, v110, v118
	v_rcp_f32_e32 v106, v105
	v_div_fmas_f32 v98, v98, v112, v99
	v_div_fixup_f32 v99, v98, v111, v119
	v_mov_b32_e32 v121, v63
	v_fma_f32 v98, -v105, v106, 1.0
	v_fmac_f32_e32 v106, v98, v106
	v_div_scale_f32 v98, vcc, v118, v110, v118
	v_mul_f32_e32 v107, v98, v106
	v_fma_f32 v108, -v105, v107, v98
	v_fmac_f32_e32 v107, v108, v106
	v_fma_f32 v98, -v105, v107, v98
	v_div_fmas_f32 v98, v98, v106, v107
	v_div_fixup_f32 v98, v98, v110, v118
	v_mov_b32_e32 v118, v54
	v_mov_b32_e32 v119, v62
	v_pk_mul_f32 v[120:121], v[120:121], v[120:121]
	v_mov_b32_e32 v114, v52
	v_mov_b32_e32 v115, v60
	v_pk_fma_f32 v[118:119], v[118:119], v[118:119], v[120:121]
	v_mov_b32_e32 v116, v53
	v_mov_b32_e32 v117, v61
	v_pk_fma_f32 v[114:115], v[114:115], v[114:115], v[118:119]
	v_mov_b32_e32 v110, v14
	v_mov_b32_e32 v111, v58
	v_pk_fma_f32 v[114:115], v[116:117], v[116:117], v[114:115]
	v_mov_b32_e32 v112, v15
	v_mov_b32_e32 v113, v59
	v_pk_fma_f32 v[110:111], v[110:111], v[110:111], v[114:115]
	v_mov_b32_e32 v106, v12
	v_mov_b32_e32 v107, v56
	v_pk_fma_f32 v[110:111], v[112:113], v[112:113], v[110:111]
	v_mov_b32_e32 v108, v13
	v_mov_b32_e32 v109, v57
	v_pk_fma_f32 v[106:107], v[106:107], v[106:107], v[110:111]
	v_add_f32_e32 v100, v100, v101
	v_pk_fma_f32 v[106:107], v[108:109], v[108:109], v[106:107]
	v_lshlrev_b32_e32 v105, 16, v0
	v_add_f32_e32 v100, v100, v106
	v_add_f32_e32 v100, v100, v107
	v_add_f32_e32 v50, v100, v50
	v_add_f32_e32 v50, v50, v51
	v_add_f32_e32 v50, v50, v82
	v_add_f32_e32 v50, v50, v83
	ds_bpermute_b32 v51, v104, v50
	v_and_b32_e32 v100, 0xffff0000, v0
	v_lshlrev_b32_e32 v104, 16, v2
	v_and_b32_e32 v0, 0xffff0000, v2
	v_lshlrev_b32_e32 v101, 16, v1
	s_waitcnt lgkmcnt(0)
	v_add_f32_e32 v2, v50, v51
	ds_bpermute_b32 v82, v103, v2
	v_mul_f32_e32 v50, 0xbfb8aa3b, v104
	v_mul_f32_e32 v51, 0xbfb8aa3b, v0
	v_exp_f32_e32 v50, v50
	v_exp_f32_e32 v51, v51
	s_waitcnt lgkmcnt(0)
	v_add_f32_e32 v2, v2, v82
	v_fmamk_f32 v2, v2, 0x3b800000, v178
	v_mul_f32_e32 v82, 0x4b800000, v2
	v_cmp_gt_f32_e32 vcc, s83, v2
	s_add_i32 s16, s16, s92
	s_add_i32 s3, s3, s18
	v_cndmask_b32_e32 v2, v2, v82, vcc
	v_rsq_f32_e32 v2, v2
	v_pk_add_f32 v[82:83], v[50:51], 1.0 op_sel_hi:[1,0]
	s_add_i32 s84, s84, s19
	v_div_scale_f32 v51, s[86:87], v83, v83, v0
	v_mul_f32_e32 v50, 0x45800000, v2
	v_cndmask_b32_e32 v50, v2, v50, vcc
	v_pk_mul_f32 v[80:81], v[50:51], v[80:81] op_sel_hi:[0,1]
	v_pk_mul_f32 v[78:79], v[50:51], v[78:79] op_sel_hi:[0,1]
	v_pk_mul_f32 v[76:77], v[50:51], v[76:77] op_sel_hi:[0,1]
	v_pk_mul_f32 v[74:75], v[50:51], v[74:75] op_sel_hi:[0,1]
	s_waitcnt vmcnt(0)
	v_mov_b32_e32 v4, v160
	v_mov_b32_e32 v5, v161
	v_mov_b32_e32 v6, v162
	v_mov_b32_e32 v7, v163
	v_mov_b32_e32 v8, v156
	v_mov_b32_e32 v9, v157
	v_mov_b32_e32 v10, v158
	v_mov_b32_e32 v11, v159
	v_pk_mul_f32 v[8:9], v[8:9], v[80:81]
	v_pk_mul_f32 v[10:11], v[10:11], v[78:79]
	v_pk_mul_f32 v[4:5], v[4:5], v[76:77]
	v_pk_mul_f32 v[6:7], v[6:7], v[74:75]
	v_pk_mul_f32 v[8:9], v[94:95], v[8:9]
	v_pk_mul_f32 v[10:11], v[90:91], v[10:11]
	v_pk_mul_f32 v[4:5], v[86:87], v[4:5]
	v_pk_mul_f32 v[6:7], v[96:97], v[6:7]
	v_cvt_pk_bf16_f32 v74, v8, v9
	v_cvt_pk_bf16_f32 v75, v10, v11
	v_cvt_pk_bf16_f32 v76, v4, v5
	v_cvt_pk_bf16_f32 v77, v6, v7
	v_rcp_f32_e32 v2, v51
	global_store_dwordx4 v[16:17], v[74:77], off
	s_nop 0
	v_and_b32_e32 v86, 0xffff0000, v1
	v_fma_f32 v1, -v51, v2, 1.0
	v_fmac_f32_e32 v2, v1, v2
	v_div_scale_f32 v1, vcc, v0, v83, v0
	v_lshlrev_b32_e32 v94, 16, v3
	v_and_b32_e32 v95, 0xffff0000, v3
	v_mul_f32_e32 v3, v1, v2
	v_fma_f32 v87, -v51, v3, v1
	v_fmac_f32_e32 v3, v87, v2
	v_fma_f32 v1, -v51, v3, v1
	v_div_scale_f32 v51, s[86:87], v82, v82, v104
	v_rcp_f32_e32 v87, v51
	v_div_fmas_f32 v1, v1, v2, v3
	v_div_fixup_f32 v83, v1, v83, v0
	v_mul_f32_e32 v1, 0xbfb8aa3b, v86
	v_fma_f32 v0, -v51, v87, 1.0
	v_fmac_f32_e32 v87, v0, v87
	v_mul_f32_e32 v0, 0xbfb8aa3b, v101
	v_exp_f32_e32 v0, v0
	v_exp_f32_e32 v1, v1
	v_div_scale_f32 v2, vcc, v104, v82, v104
	v_mul_f32_e32 v3, v2, v87
	v_fma_f32 v90, -v51, v3, v2
	v_fmac_f32_e32 v3, v90, v87
	v_pk_add_f32 v[0:1], v[0:1], 1.0 op_sel_hi:[1,0]
	v_fma_f32 v2, -v51, v3, v2
	v_div_scale_f32 v51, s[86:87], v1, v1, v86
	v_rcp_f32_e32 v90, v51
	v_div_fmas_f32 v2, v2, v87, v3
	v_div_fixup_f32 v82, v2, v82, v104
	s_cmpk_gt_i32 s16, 0x7ff
	v_fma_f32 v2, -v51, v90, 1.0
	v_fmac_f32_e32 v90, v2, v90
	v_div_scale_f32 v2, vcc, v86, v1, v86
	v_mul_f32_e32 v3, v2, v90
	v_fma_f32 v87, -v51, v3, v2
	v_fmac_f32_e32 v3, v87, v90
	v_fma_f32 v2, -v51, v3, v2
	v_div_scale_f32 v51, s[86:87], v0, v0, v101
	v_rcp_f32_e32 v96, v51
	v_div_fmas_f32 v2, v2, v90, v3
	v_div_fixup_f32 v87, v2, v1, v86
	v_mul_f32_e32 v2, 0xbfb8aa3b, v105
	v_mul_f32_e32 v3, 0xbfb8aa3b, v100
	v_fma_f32 v1, -v51, v96, 1.0
	v_exp_f32_e32 v2, v2
	v_exp_f32_e32 v3, v3
	v_fmac_f32_e32 v96, v1, v96
	v_div_scale_f32 v1, vcc, v101, v0, v101
	v_mul_f32_e32 v86, v1, v96
	v_fma_f32 v90, -v51, v86, v1
	v_fmac_f32_e32 v86, v90, v96
	v_pk_add_f32 v[90:91], v[2:3], 1.0 op_sel_hi:[1,0]
	v_fma_f32 v1, -v51, v86, v1
	v_div_scale_f32 v2, s[86:87], v91, v91, v100
	v_rcp_f32_e32 v51, v2
	v_div_fmas_f32 v1, v1, v96, v86
	v_div_fixup_f32 v86, v1, v0, v101
	v_fma_f32 v0, -v2, v51, 1.0
	v_fmac_f32_e32 v51, v0, v51
	v_div_scale_f32 v0, vcc, v100, v91, v100
	v_mul_f32_e32 v96, v0, v51
	v_fma_f32 v1, -v2, v96, v0
	v_fmac_f32_e32 v96, v1, v51
	v_fma_f32 v97, -v2, v96, v0
	v_pk_mul_f32 v[0:1], v[50:51], v[72:73] op_sel_hi:[0,1]
	v_pk_mul_f32 v[2:3], v[50:51], v[70:71] op_sel_hi:[0,1]
	v_pk_mul_f32 v[68:69], v[50:51], v[68:69] op_sel_hi:[0,1]
	v_pk_mul_f32 v[66:67], v[50:51], v[66:67] op_sel_hi:[0,1]
	s_waitcnt vmcnt(0)
	v_mov_b32_e32 v4, v136
	v_mov_b32_e32 v5, v137
	v_mov_b32_e32 v6, v138
	v_mov_b32_e32 v7, v139
	v_mov_b32_e32 v8, v140
	v_mov_b32_e32 v9, v141
	v_mov_b32_e32 v10, v142
	v_mov_b32_e32 v11, v143
	v_mov_b32_e32 v74, v184
	v_mov_b32_e32 v75, v185
	v_mov_b32_e32 v76, v186
	v_mov_b32_e32 v77, v187
	v_mov_b32_e32 v78, v168
	v_mov_b32_e32 v79, v169
	v_mov_b32_e32 v80, v170
	v_mov_b32_e32 v81, v171
	v_pk_mul_f32 v[0:1], v[0:1], v[78:79]
	v_pk_mul_f32 v[2:3], v[2:3], v[80:81]
	v_pk_mul_f32 v[68:69], v[68:69], v[74:75]
	v_pk_mul_f32 v[66:67], v[66:67], v[76:77]
	v_pk_mul_f32 v[0:1], v[0:1], v[92:93]
	v_pk_mul_f32 v[2:3], v[2:3], v[88:89]
	v_pk_mul_f32 v[68:69], v[84:85], v[68:69]
	v_pk_mul_f32 v[66:67], v[98:99], v[66:67]
	v_cvt_pk_bf16_f32 v0, v0, v1
	v_cvt_pk_bf16_f32 v1, v2, v3
	v_cvt_pk_bf16_f32 v2, v68, v69
	v_cvt_pk_bf16_f32 v3, v66, v67
	global_store_dwordx4 v[16:17], v[0:3], off offset:16
	s_nop 0
	v_div_scale_f32 v70, s[86:87], v90, v90, v105
	v_rcp_f32_e32 v74, v70
	v_mul_f32_e32 v72, 0xbfb8aa3b, v94
	v_mul_f32_e32 v73, 0xbfb8aa3b, v95
	v_div_fmas_f32 v51, v97, v51, v96
	v_exp_f32_e32 v72, v72
	v_exp_f32_e32 v73, v73
	v_div_fixup_f32 v71, v51, v91, v100
	v_fma_f32 v51, -v70, v74, 1.0
	v_fmac_f32_e32 v74, v51, v74
	v_div_scale_f32 v51, vcc, v105, v90, v105
	v_mul_f32_e32 v75, v51, v74
	v_fma_f32 v76, -v70, v75, v51
	v_pk_add_f32 v[72:73], v[72:73], 1.0 op_sel_hi:[1,0]
	v_fmac_f32_e32 v75, v76, v74
	v_div_scale_f32 v76, s[86:87], v73, v73, v95
	v_rcp_f32_e32 v77, v76
	v_fma_f32 v51, -v70, v75, v51
	v_div_fmas_f32 v51, v51, v74, v75
	v_div_fixup_f32 v70, v51, v90, v105
	v_fma_f32 v51, -v76, v77, 1.0
	v_fmac_f32_e32 v77, v51, v77
	v_div_scale_f32 v51, vcc, v95, v73, v95
	v_mul_f32_e32 v74, v51, v77
	v_fma_f32 v75, -v76, v74, v51
	v_fmac_f32_e32 v74, v75, v77
	v_div_scale_f32 v75, s[86:87], v72, v72, v94
	v_fma_f32 v51, -v76, v74, v51
	v_rcp_f32_e32 v76, v75
	v_div_fmas_f32 v51, v51, v77, v74
	v_div_fixup_f32 v73, v51, v73, v95
	v_and_b32_e32 v78, 0xffff0000, v4
	v_fma_f32 v51, -v75, v76, 1.0
	v_fmac_f32_e32 v76, v51, v76
	v_div_scale_f32 v51, vcc, v94, v72, v94
	v_mul_f32_e32 v74, v51, v76
	v_fma_f32 v77, -v75, v74, v51
	v_fmac_f32_e32 v74, v77, v76
	v_fma_f32 v51, -v75, v74, v51
	v_div_fmas_f32 v51, v51, v76, v74
	v_div_fixup_f32 v72, v51, v72, v94
	v_lshlrev_b32_e32 v51, 16, v6
	v_and_b32_e32 v76, 0xffff0000, v6
	v_mul_f32_e32 v6, 0xbfb8aa3b, v51
	v_exp_f32_e32 v74, v6
	v_mul_f32_e32 v6, 0xbfb8aa3b, v76
	v_exp_f32_e32 v75, v6
	v_lshlrev_b32_e32 v77, 16, v4
	v_lshlrev_b32_e32 v79, 16, v5
	v_and_b32_e32 v80, 0xffff0000, v5
	v_pk_add_f32 v[74:75], v[74:75], 1.0 op_sel_hi:[1,0]
	v_lshlrev_b32_e32 v81, 16, v7
	v_div_scale_f32 v4, s[86:87], v75, v75, v76
	v_rcp_f32_e32 v6, v4
	v_and_b32_e32 v84, 0xffff0000, v7
	v_pk_mul_f32 v[14:15], v[50:51], v[14:15] op_sel_hi:[0,1]
	v_div_scale_f32 v88, s[86:87], v74, v74, v51
	v_fma_f32 v5, -v4, v6, 1.0
	v_fmac_f32_e32 v6, v5, v6
	v_div_scale_f32 v5, vcc, v76, v75, v76
	v_mul_f32_e32 v7, v5, v6
	v_fma_f32 v85, -v4, v7, v5
	v_fmac_f32_e32 v7, v85, v6
	v_fma_f32 v4, -v4, v7, v5
	v_div_fmas_f32 v85, v4, v6, v7
	v_pk_mul_f32 v[4:5], v[50:51], v[54:55] op_sel_hi:[0,1]
	v_pk_mul_f32 v[6:7], v[50:51], v[52:53] op_sel_hi:[0,1]
	v_rcp_f32_e32 v89, v88
	s_waitcnt vmcnt(1)
	v_mov_b32_e32 v0, v192
	v_mov_b32_e32 v1, v193
	v_mov_b32_e32 v2, v194
	v_mov_b32_e32 v3, v195
	v_pk_mul_f32 v[0:1], v[14:15], v[0:1]
	s_nop 0
	v_pk_mul_f32 v[14:15], v[82:83], v[0:1]
	v_pk_mul_f32 v[0:1], v[50:51], v[12:13] op_sel_hi:[0,1]
	s_waitcnt vmcnt(0)
	v_mov_b32_e32 v66, v188
	v_mov_b32_e32 v67, v189
	v_mov_b32_e32 v68, v190
	v_mov_b32_e32 v69, v191
	v_pk_mul_f32 v[4:5], v[4:5], v[66:67]
	v_pk_mul_f32 v[6:7], v[6:7], v[68:69]
	v_pk_mul_f32 v[0:1], v[0:1], v[2:3]
	v_pk_mul_f32 v[4:5], v[4:5], v[70:71]
	v_pk_mul_f32 v[6:7], v[6:7], v[86:87]
	v_pk_mul_f32 v[12:13], v[72:73], v[0:1]
	v_cvt_pk_bf16_f32 v0, v4, v5
	v_cvt_pk_bf16_f32 v1, v6, v7
	v_cvt_pk_bf16_f32 v2, v14, v15
	v_cvt_pk_bf16_f32 v3, v12, v13
	global_store_dwordx4 v[16:17], v[0:3], off offset:32
	s_nop 0
	v_mul_f32_e32 v14, 0xbfb8aa3b, v79
	v_mul_f32_e32 v15, 0xbfb8aa3b, v80
	v_exp_f32_e32 v14, v14
	v_exp_f32_e32 v15, v15
	v_fma_f32 v12, -v88, v89, 1.0
	v_fmac_f32_e32 v89, v12, v89
	v_div_scale_f32 v12, vcc, v51, v74, v51
	v_mul_f32_e32 v52, v12, v89
	v_fma_f32 v53, -v88, v52, v12
	v_pk_add_f32 v[14:15], v[14:15], 1.0 op_sel_hi:[1,0]
	v_fmac_f32_e32 v52, v53, v89
	v_div_scale_f32 v53, s[86:87], v15, v15, v80
	v_rcp_f32_e32 v54, v53
	v_fma_f32 v12, -v88, v52, v12
	v_div_fmas_f32 v12, v12, v89, v52
	v_div_fixup_f32 v12, v12, v74, v51
	v_fma_f32 v51, -v53, v54, 1.0
	v_fmac_f32_e32 v54, v51, v54
	v_div_scale_f32 v51, vcc, v80, v15, v80
	v_mul_f32_e32 v52, v51, v54
	v_fma_f32 v55, -v53, v52, v51
	v_fmac_f32_e32 v52, v55, v54
	v_div_scale_f32 v55, s[86:87], v14, v14, v79
	v_rcp_f32_e32 v66, v55
	v_fma_f32 v51, -v53, v52, v51
	v_div_fmas_f32 v51, v51, v54, v52
	v_mul_f32_e32 v52, 0xbfb8aa3b, v77
	v_mul_f32_e32 v53, 0xbfb8aa3b, v78
	v_div_fixup_f32 v15, v51, v15, v80
	v_fma_f32 v51, -v55, v66, 1.0
	v_exp_f32_e32 v52, v52
	v_exp_f32_e32 v53, v53
	v_fmac_f32_e32 v66, v51, v66
	v_div_scale_f32 v51, vcc, v79, v14, v79
	v_mul_f32_e32 v54, v51, v66
	v_fma_f32 v67, -v55, v54, v51
	v_fmac_f32_e32 v54, v67, v66
	v_pk_add_f32 v[52:53], v[52:53], 1.0 op_sel_hi:[1,0]
	v_fma_f32 v51, -v55, v54, v51
	v_div_scale_f32 v55, s[86:87], v53, v53, v78
	v_rcp_f32_e32 v67, v55
	v_div_fmas_f32 v51, v51, v66, v54
	v_div_fixup_f32 v14, v51, v14, v79
	v_div_fixup_f32 v13, v85, v75, v76
	v_fma_f32 v51, -v55, v67, 1.0
	v_fmac_f32_e32 v67, v51, v67
	v_div_scale_f32 v51, vcc, v78, v53, v78
	v_mul_f32_e32 v54, v51, v67
	v_fma_f32 v66, -v55, v54, v51
	v_fmac_f32_e32 v54, v66, v67
	v_fma_f32 v51, -v55, v54, v51
	v_div_scale_f32 v55, s[86:87], v52, v52, v77
	v_rcp_f32_e32 v66, v55
	v_div_fmas_f32 v51, v51, v67, v54
	v_div_fixup_f32 v53, v51, v53, v78
	v_fma_f32 v51, -v55, v66, 1.0
	v_fmac_f32_e32 v66, v51, v66
	v_div_scale_f32 v51, vcc, v77, v52, v77
	v_mul_f32_e32 v54, v51, v66
	v_fma_f32 v67, -v55, v54, v51
	v_fmac_f32_e32 v54, v67, v66
	v_fma_f32 v51, -v55, v54, v51
	v_div_fmas_f32 v51, v51, v66, v54
	v_pk_mul_f32 v[54:55], v[50:51], v[62:63] op_sel_hi:[0,1]
	v_div_fixup_f32 v52, v51, v52, v77
	v_and_b32_e32 v62, 0xffff0000, v9
	v_lshlrev_b32_e32 v63, 16, v10
	v_and_b32_e32 v66, 0xffff0000, v11
	s_waitcnt vmcnt(0)
	v_mov_b32_e32 v0, v200
	v_mov_b32_e32 v1, v201
	v_mov_b32_e32 v2, v202
	v_mov_b32_e32 v3, v203
	v_mov_b32_e32 v4, v196
	v_mov_b32_e32 v5, v197
	v_mov_b32_e32 v6, v198
	v_mov_b32_e32 v7, v199
	v_pk_mul_f32 v[4:5], v[54:55], v[4:5]
	s_nop 0
	v_pk_mul_f32 v[4:5], v[4:5], v[52:53]
	v_pk_mul_f32 v[52:53], v[50:51], v[60:61] op_sel_hi:[0,1]
	v_mul_f32_e32 v51, 0xbfb8aa3b, v81
	v_pk_mul_f32 v[6:7], v[52:53], v[6:7]
	v_exp_f32_e32 v52, v51
	v_mul_f32_e32 v51, 0xbfb8aa3b, v84
	v_exp_f32_e32 v53, v51
	v_pk_mul_f32 v[6:7], v[6:7], v[14:15]
	v_pk_mul_f32 v[14:15], v[50:51], v[58:59] op_sel_hi:[0,1]
	v_pk_mul_f32 v[0:1], v[14:15], v[0:1]
	v_pk_add_f32 v[14:15], v[52:53], 1.0 op_sel_hi:[1,0]
	v_pk_mul_f32 v[12:13], v[12:13], v[0:1]
	v_div_scale_f32 v51, s[86:87], v15, v15, v84
	v_rcp_f32_e32 v52, v51
	v_pk_mul_f32 v[0:1], v[50:51], v[56:57] op_sel_hi:[0,1]
	v_pk_mul_f32 v[0:1], v[0:1], v[2:3]
	v_and_b32_e32 v60, 0xffff0000, v8
	v_fma_f32 v2, -v51, v52, 1.0
	v_fmac_f32_e32 v52, v2, v52
	v_div_scale_f32 v2, vcc, v84, v15, v84
	v_mul_f32_e32 v3, v2, v52
	v_fma_f32 v53, -v51, v3, v2
	v_fmac_f32_e32 v3, v53, v52
	v_fma_f32 v2, -v51, v3, v2
	v_div_scale_f32 v51, s[86:87], v14, v14, v81
	v_rcp_f32_e32 v53, v51
	v_div_fmas_f32 v2, v2, v52, v3
	v_div_fixup_f32 v3, v2, v15, v84
	v_lshlrev_b32_e32 v61, 16, v9
	v_fma_f32 v2, -v51, v53, 1.0
	v_fmac_f32_e32 v53, v2, v53
	v_div_scale_f32 v2, vcc, v81, v14, v81
	v_mul_f32_e32 v15, v2, v53
	v_fma_f32 v52, -v51, v15, v2
	v_fmac_f32_e32 v15, v52, v53
	v_fma_f32 v2, -v51, v15, v2
	v_div_fmas_f32 v2, v2, v53, v15
	v_div_fixup_f32 v2, v2, v14, v81
	v_pk_mul_f32 v[14:15], v[2:3], v[0:1]
	v_cvt_pk_bf16_f32 v0, v4, v5
	v_cvt_pk_bf16_f32 v1, v6, v7
	v_cvt_pk_bf16_f32 v2, v12, v13
	v_cvt_pk_bf16_f32 v3, v14, v15
	global_store_dwordx4 v[16:17], v[0:3], off offset:48
	s_nop 0
	v_lshlrev_b32_e32 v51, 16, v8
	v_mul_f32_e32 v8, 0xbfb8aa3b, v51
	v_mul_f32_e32 v9, 0xbfb8aa3b, v60
	v_exp_f32_e32 v8, v8
	v_exp_f32_e32 v9, v9
	v_and_b32_e32 v64, 0xffff0000, v10
	v_mov_b32_e32 v10, v46
	v_lshlrev_b32_e32 v65, 16, v11
	v_pk_add_f32 v[8:9], v[8:9], 1.0 op_sel_hi:[1,0]
	v_mov_b32_e32 v11, v48
	v_div_scale_f32 v46, s[86:87], v9, v9, v60
	v_rcp_f32_e32 v67, v46
	v_pk_mul_f32 v[10:11], v[50:51], v[10:11] op_sel_hi:[0,1]
	v_fma_f32 v48, -v46, v67, 1.0
	v_fmac_f32_e32 v67, v48, v67
	v_div_scale_f32 v48, vcc, v60, v9, v60
	s_waitcnt vmcnt(4)
	v_mov_b32_e32 v52, v208
	v_mov_b32_e32 v53, v209
	v_mov_b32_e32 v54, v210
	v_mov_b32_e32 v55, v211
	v_pk_mul_f32 v[10:11], v[10:11], v[52:53]
	v_mul_f32_e32 v52, v48, v67
	v_fma_f32 v53, -v46, v52, v48
	v_fmac_f32_e32 v52, v53, v67
	v_fma_f32 v46, -v46, v52, v48
	v_div_scale_f32 v48, s[86:87], v8, v8, v51
	v_rcp_f32_e32 v53, v48
	v_div_fmas_f32 v46, v46, v67, v52
	v_div_fixup_f32 v9, v46, v9, v60
	v_fma_f32 v46, -v48, v53, 1.0
	v_fmac_f32_e32 v53, v46, v53
	v_div_scale_f32 v46, vcc, v51, v8, v51
	v_mul_f32_e32 v52, v46, v53
	v_fma_f32 v60, -v48, v52, v46
	v_fmac_f32_e32 v52, v60, v53
	v_fma_f32 v46, -v48, v52, v46
	v_mul_f32_e32 v48, 0xbfb8aa3b, v61
	v_div_fmas_f32 v46, v46, v53, v52
	v_exp_f32_e32 v52, v48
	v_mul_f32_e32 v48, 0xbfb8aa3b, v62
	v_exp_f32_e32 v53, v48
	v_div_fixup_f32 v8, v46, v8, v51
	v_pk_mul_f32 v[8:9], v[10:11], v[8:9]
	v_mov_b32_e32 v10, v42
	v_pk_add_f32 v[52:53], v[52:53], 1.0 op_sel_hi:[1,0]
	v_mov_b32_e32 v11, v44
	v_div_scale_f32 v42, s[86:87], v53, v53, v62
	v_rcp_f32_e32 v46, v42
	v_pk_mul_f32 v[10:11], v[50:51], v[10:11] op_sel_hi:[0,1]
	v_pk_mul_f32 v[10:11], v[10:11], v[54:55]
	v_cvt_pk_bf16_f32 v8, v8, v9
	v_fma_f32 v44, -v42, v46, 1.0
	v_fmac_f32_e32 v46, v44, v46
	v_div_scale_f32 v44, vcc, v62, v53, v62
	v_mul_f32_e32 v48, v44, v46
	v_fma_f32 v51, -v42, v48, v44
	v_fmac_f32_e32 v48, v51, v46
	v_fma_f32 v42, -v42, v48, v44
	v_div_scale_f32 v44, s[86:87], v52, v52, v61
	v_rcp_f32_e32 v51, v44
	v_div_fmas_f32 v42, v42, v46, v48
	v_div_fixup_f32 v53, v42, v53, v62
	v_fma_f32 v42, -v44, v51, 1.0
	v_fmac_f32_e32 v51, v42, v51
	v_div_scale_f32 v42, vcc, v61, v52, v61
	v_mul_f32_e32 v46, v42, v51
	v_fma_f32 v48, -v44, v46, v42
	v_fmac_f32_e32 v46, v48, v51
	v_fma_f32 v42, -v44, v46, v42
	v_mul_f32_e32 v44, 0xbfb8aa3b, v63
	v_exp_f32_e32 v54, v44
	v_mul_f32_e32 v44, 0xbfb8aa3b, v64
	v_exp_f32_e32 v55, v44
	v_div_fmas_f32 v42, v42, v51, v46
	v_div_fixup_f32 v52, v42, v52, v61
	v_pk_mul_f32 v[10:11], v[10:11], v[52:53]
	v_pk_add_f32 v[54:55], v[54:55], 1.0 op_sel_hi:[1,0]
	v_mov_b32_e32 v52, v38
	v_div_scale_f32 v38, s[86:87], v55, v55, v64
	v_rcp_f32_e32 v42, v38
	v_mov_b32_e32 v53, v40
	v_pk_mul_f32 v[52:53], v[50:51], v[52:53] op_sel_hi:[0,1]
	s_waitcnt vmcnt(3)
	v_mov_b32_e32 v56, v212
	v_mov_b32_e32 v57, v213
	v_mov_b32_e32 v58, v214
	v_mov_b32_e32 v59, v215
	v_pk_mul_f32 v[52:53], v[52:53], v[56:57]
	v_fma_f32 v40, -v38, v42, 1.0
	v_fmac_f32_e32 v42, v40, v42
	v_div_scale_f32 v40, vcc, v64, v55, v64
	v_mul_f32_e32 v44, v40, v42
	v_fma_f32 v46, -v38, v44, v40
	v_fmac_f32_e32 v44, v46, v42
	v_fma_f32 v38, -v38, v44, v40
	v_div_scale_f32 v40, s[86:87], v54, v54, v63
	v_rcp_f32_e32 v46, v40
	v_div_fmas_f32 v38, v38, v42, v44
	v_div_fixup_f32 v55, v38, v55, v64
	v_cvt_pk_bf16_f32 v9, v10, v11
	v_fma_f32 v38, -v40, v46, 1.0
	v_fmac_f32_e32 v46, v38, v46
	v_div_scale_f32 v38, vcc, v63, v54, v63
	v_mul_f32_e32 v42, v38, v46
	v_fma_f32 v44, -v40, v42, v38
	v_fmac_f32_e32 v42, v44, v46
	v_fma_f32 v38, -v40, v42, v38
	v_mul_f32_e32 v40, 0xbfb8aa3b, v65
	v_exp_f32_e32 v56, v40
	v_mul_f32_e32 v40, 0xbfb8aa3b, v66
	v_exp_f32_e32 v57, v40
	v_div_fmas_f32 v38, v38, v46, v42
	v_div_fixup_f32 v54, v38, v54, v63
	v_pk_mul_f32 v[52:53], v[54:55], v[52:53]
	v_pk_add_f32 v[56:57], v[56:57], 1.0 op_sel_hi:[1,0]
	v_mov_b32_e32 v54, v34
	v_div_scale_f32 v34, s[86:87], v57, v57, v66
	v_rcp_f32_e32 v38, v34
	v_mov_b32_e32 v55, v36
	v_pk_mul_f32 v[54:55], v[50:51], v[54:55] op_sel_hi:[0,1]
	v_pk_mul_f32 v[54:55], v[54:55], v[58:59]
	v_fma_f32 v36, -v34, v38, 1.0
	v_fmac_f32_e32 v38, v36, v38
	v_div_scale_f32 v36, vcc, v66, v57, v66
	v_mul_f32_e32 v40, v36, v38
	v_fma_f32 v42, -v34, v40, v36
	v_fmac_f32_e32 v40, v42, v38
	v_fma_f32 v34, -v34, v40, v36
	v_div_scale_f32 v36, s[86:87], v56, v56, v65
	v_rcp_f32_e32 v42, v36
	v_div_fmas_f32 v34, v34, v38, v40
	v_div_fixup_f32 v57, v34, v57, v66
	v_cvt_pk_bf16_f32 v10, v52, v53
	v_fma_f32 v34, -v36, v42, 1.0
	v_fmac_f32_e32 v42, v34, v42
	v_div_scale_f32 v34, vcc, v65, v56, v65
	v_mul_f32_e32 v38, v34, v42
	v_fma_f32 v40, -v36, v38, v34
	v_fmac_f32_e32 v38, v40, v42
	v_fma_f32 v34, -v36, v38, v34
	v_div_fmas_f32 v34, v34, v42, v38
	v_div_fixup_f32 v56, v34, v56, v65
	v_pk_mul_f32 v[54:55], v[56:57], v[54:55]
	s_waitcnt vmcnt(0)
	v_mov_b32_e32 v0, v152
	v_mov_b32_e32 v1, v153
	v_mov_b32_e32 v2, v154
	v_mov_b32_e32 v3, v155
	v_mov_b32_e32 v4, v148
	v_mov_b32_e32 v5, v149
	v_mov_b32_e32 v6, v150
	v_mov_b32_e32 v7, v151
	v_mov_b32_e32 v12, v144
	v_mov_b32_e32 v13, v145
	v_mov_b32_e32 v14, v146
	v_mov_b32_e32 v15, v147
	v_lshlrev_b32_e32 v34, 16, v12
	v_cvt_pk_bf16_f32 v11, v54, v55
	global_store_dwordx4 v[16:17], v[8:11], off offset:64
	s_nop 0
	v_and_b32_e32 v36, 0xffff0000, v12
	v_lshlrev_b32_e32 v38, 16, v13
	v_and_b32_e32 v40, 0xffff0000, v13
	v_mul_f32_e32 v12, 0xbfb8aa3b, v34
	v_mul_f32_e32 v13, 0xbfb8aa3b, v36
	v_exp_f32_e32 v12, v12
	v_exp_f32_e32 v13, v13
	v_lshlrev_b32_e32 v51, 16, v15
	v_mov_b32_e32 v48, v47
	v_lshlrev_b32_e32 v42, 16, v14
	v_pk_add_f32 v[12:13], v[12:13], 1.0 op_sel_hi:[1,0]
	v_and_b32_e32 v46, 0xffff0000, v14
	v_div_scale_f32 v44, s[86:87], v13, v13, v36
	v_rcp_f32_e32 v57, v44
	v_and_b32_e32 v56, 0xffff0000, v15
	v_pk_mul_f32 v[14:15], v[50:51], v[48:49] op_sel_hi:[0,1]
	s_waitcnt vmcnt(1)
	v_mov_b32_e32 v8, v216
	v_mov_b32_e32 v9, v217
	v_mov_b32_e32 v10, v218
	v_mov_b32_e32 v11, v219
	v_pk_mul_f32 v[8:9], v[14:15], v[8:9]
	v_fma_f32 v14, -v44, v57, 1.0
	v_fmac_f32_e32 v57, v14, v57
	v_div_scale_f32 v14, vcc, v36, v13, v36
	v_mul_f32_e32 v15, v14, v57
	v_fma_f32 v47, -v44, v15, v14
	v_fmac_f32_e32 v15, v47, v57
	v_fma_f32 v14, -v44, v15, v14
	v_div_scale_f32 v44, s[86:87], v12, v12, v34
	v_rcp_f32_e32 v47, v44
	v_div_fmas_f32 v14, v14, v57, v15
	v_div_fixup_f32 v13, v14, v13, v36
	v_fma_f32 v14, -v44, v47, 1.0
	v_fmac_f32_e32 v47, v14, v47
	v_div_scale_f32 v14, vcc, v34, v12, v34
	v_mul_f32_e32 v36, v14, v47
	v_fma_f32 v15, -v44, v36, v14
	v_fmac_f32_e32 v36, v15, v47
	v_fma_f32 v44, -v44, v36, v14
	v_mul_f32_e32 v14, 0xbfb8aa3b, v38
	v_mul_f32_e32 v15, 0xbfb8aa3b, v40
	v_exp_f32_e32 v14, v14
	v_exp_f32_e32 v15, v15
	v_div_fmas_f32 v36, v44, v47, v36
	v_div_fixup_f32 v12, v36, v12, v34
	v_pk_mul_f32 v[8:9], v[8:9], v[12:13]
	v_pk_add_f32 v[12:13], v[14:15], 1.0 op_sel_hi:[1,0]
	v_mov_b32_e32 v44, v43
	v_div_scale_f32 v34, s[86:87], v13, v13, v40
	v_rcp_f32_e32 v36, v34
	v_pk_mul_f32 v[14:15], v[50:51], v[44:45] op_sel_hi:[0,1]
	v_pk_mul_f32 v[10:11], v[14:15], v[10:11]
	v_cvt_pk_bf16_f32 v8, v8, v9
	v_fma_f32 v14, -v34, v36, 1.0
	v_fmac_f32_e32 v36, v14, v36
	v_div_scale_f32 v14, vcc, v40, v13, v40
	v_mul_f32_e32 v15, v14, v36
	v_fma_f32 v43, -v34, v15, v14
	v_fmac_f32_e32 v15, v43, v36
	v_fma_f32 v14, -v34, v15, v14
	v_div_scale_f32 v34, s[86:87], v12, v12, v38
	v_rcp_f32_e32 v43, v34
	v_div_fmas_f32 v14, v14, v36, v15
	v_div_fixup_f32 v13, v14, v13, v40
	v_mov_b32_e32 v40, v39
	v_fma_f32 v14, -v34, v43, 1.0
	v_fmac_f32_e32 v43, v14, v43
	v_div_scale_f32 v14, vcc, v38, v12, v38
	v_mul_f32_e32 v36, v14, v43
	v_fma_f32 v15, -v34, v36, v14
	v_fmac_f32_e32 v36, v15, v43
	v_fma_f32 v34, -v34, v36, v14
	v_mul_f32_e32 v14, 0xbfb8aa3b, v42
	v_mul_f32_e32 v15, 0xbfb8aa3b, v46
	v_exp_f32_e32 v14, v14
	v_exp_f32_e32 v15, v15
	v_div_fmas_f32 v34, v34, v43, v36
	v_div_fixup_f32 v12, v34, v12, v38
	v_pk_mul_f32 v[10:11], v[10:11], v[12:13]
	v_pk_add_f32 v[12:13], v[14:15], 1.0 op_sel_hi:[1,0]
	v_pk_mul_f32 v[14:15], v[50:51], v[40:41] op_sel_hi:[0,1]
	v_div_scale_f32 v34, s[86:87], v13, v13, v46
	v_rcp_f32_e32 v36, v34
	s_waitcnt vmcnt(0)
	v_mov_b32_e32 v52, v220
	v_mov_b32_e32 v53, v221
	v_mov_b32_e32 v54, v222
	v_mov_b32_e32 v55, v223
	v_pk_mul_f32 v[14:15], v[14:15], v[52:53]
	v_cvt_pk_bf16_f32 v9, v10, v11
	v_and_b32_e32 v41, 0xffff0000, v7
	v_fma_f32 v38, -v34, v36, 1.0
	v_fmac_f32_e32 v36, v38, v36
	v_div_scale_f32 v38, vcc, v46, v13, v46
	v_mul_f32_e32 v39, v38, v36
	v_fma_f32 v40, -v34, v39, v38
	v_fmac_f32_e32 v39, v40, v36
	v_fma_f32 v34, -v34, v39, v38
	v_div_scale_f32 v38, s[86:87], v12, v12, v42
	v_rcp_f32_e32 v40, v38
	v_div_fmas_f32 v34, v34, v36, v39
	v_div_fixup_f32 v13, v34, v13, v46
	v_fma_f32 v34, -v38, v40, 1.0
	v_fmac_f32_e32 v40, v34, v40
	v_div_scale_f32 v34, vcc, v42, v12, v42
	v_mul_f32_e32 v36, v34, v40
	v_fma_f32 v39, -v38, v36, v34
	v_fmac_f32_e32 v36, v39, v40
	v_fma_f32 v34, -v38, v36, v34
	v_mul_f32_e32 v38, 0xbfb8aa3b, v51
	v_mul_f32_e32 v39, 0xbfb8aa3b, v56
	v_exp_f32_e32 v38, v38
	v_exp_f32_e32 v39, v39
	v_div_fmas_f32 v34, v34, v40, v36
	v_div_fixup_f32 v12, v34, v12, v42
	v_pk_mul_f32 v[12:13], v[12:13], v[14:15]
	v_pk_add_f32 v[14:15], v[38:39], 1.0 op_sel_hi:[1,0]
	v_mov_b32_e32 v36, v35
	v_div_scale_f32 v38, s[86:87], v15, v15, v56
	v_rcp_f32_e32 v39, v38
	v_pk_mul_f32 v[34:35], v[50:51], v[36:37] op_sel_hi:[0,1]
	v_pk_mul_f32 v[34:35], v[34:35], v[54:55]
	v_cvt_pk_bf16_f32 v10, v12, v13
	v_fma_f32 v36, -v38, v39, 1.0
	v_fmac_f32_e32 v39, v36, v39
	v_div_scale_f32 v36, vcc, v56, v15, v56
	v_mul_f32_e32 v37, v36, v39
	v_fma_f32 v40, -v38, v37, v36
	v_fmac_f32_e32 v37, v40, v39
	v_fma_f32 v36, -v38, v37, v36
	v_div_scale_f32 v38, s[86:87], v14, v14, v51
	v_rcp_f32_e32 v40, v38
	v_div_fmas_f32 v36, v36, v39, v37
	v_div_fixup_f32 v15, v36, v15, v56
	v_fma_f32 v36, -v38, v40, 1.0
	v_fmac_f32_e32 v40, v36, v40
	v_div_scale_f32 v36, vcc, v51, v14, v51
	v_mul_f32_e32 v37, v36, v40
	v_fma_f32 v39, -v38, v37, v36
	v_fmac_f32_e32 v37, v39, v40
	v_fma_f32 v36, -v38, v37, v36
	v_div_fmas_f32 v36, v36, v40, v37
	v_div_fixup_f32 v14, v36, v14, v51
	v_pk_mul_f32 v[14:15], v[14:15], v[34:35]
	v_lshlrev_b32_e32 v34, 16, v4
	v_cvt_pk_bf16_f32 v11, v14, v15
	global_store_dwordx4 v[16:17], v[8:11], off offset:80
	s_nop 0
	v_and_b32_e32 v35, 0xffff0000, v4
	v_lshlrev_b32_e32 v36, 16, v5
	v_and_b32_e32 v37, 0xffff0000, v5
	v_mul_f32_e32 v4, 0xbfb8aa3b, v34
	v_mul_f32_e32 v5, 0xbfb8aa3b, v35
	v_exp_f32_e32 v4, v4
	v_exp_f32_e32 v5, v5
	v_lshlrev_b32_e32 v38, 16, v6
	v_and_b32_e32 v39, 0xffff0000, v6
	v_mov_b32_e32 v6, v30
	v_pk_add_f32 v[4:5], v[4:5], 1.0 op_sel_hi:[1,0]
	v_lshlrev_b32_e32 v40, 16, v7
	v_div_scale_f32 v30, s[86:87], v5, v5, v35
	v_rcp_f32_e32 v42, v30
	v_mov_b32_e32 v7, v32
	v_pk_mul_f32 v[6:7], v[50:51], v[6:7] op_sel_hi:[0,1]
	s_waitcnt vmcnt(1)
	v_mov_b32_e32 v8, v224
	v_mov_b32_e32 v9, v225
	v_mov_b32_e32 v10, v226
	v_mov_b32_e32 v11, v227
	v_pk_mul_f32 v[6:7], v[6:7], v[8:9]
	v_fma_f32 v8, -v30, v42, 1.0
	v_fmac_f32_e32 v42, v8, v42
	v_div_scale_f32 v8, vcc, v35, v5, v35
	v_mul_f32_e32 v9, v8, v42
	v_fma_f32 v32, -v30, v9, v8
	v_fmac_f32_e32 v9, v32, v42
	v_fma_f32 v8, -v30, v9, v8
	v_div_scale_f32 v30, s[86:87], v4, v4, v34
	v_rcp_f32_e32 v32, v30
	v_div_fmas_f32 v8, v8, v42, v9
	v_div_fixup_f32 v5, v8, v5, v35
	v_fma_f32 v8, -v30, v32, 1.0
	v_fmac_f32_e32 v32, v8, v32
	v_div_scale_f32 v8, vcc, v34, v4, v34
	v_mul_f32_e32 v9, v8, v32
	v_fma_f32 v35, -v30, v9, v8
	v_fmac_f32_e32 v9, v35, v32
	v_fma_f32 v8, -v30, v9, v8
	v_div_fmas_f32 v30, v8, v32, v9
	v_mul_f32_e32 v8, 0xbfb8aa3b, v36
	v_mul_f32_e32 v9, 0xbfb8aa3b, v37
	v_exp_f32_e32 v8, v8
	v_exp_f32_e32 v9, v9
	v_div_fixup_f32 v4, v30, v4, v34
	v_pk_mul_f32 v[4:5], v[6:7], v[4:5]
	v_mov_b32_e32 v6, v26
	v_pk_add_f32 v[8:9], v[8:9], 1.0 op_sel_hi:[1,0]
	v_mov_b32_e32 v7, v28
	v_div_scale_f32 v26, s[86:87], v9, v9, v37
	v_rcp_f32_e32 v30, v26
	v_pk_mul_f32 v[6:7], v[50:51], v[6:7] op_sel_hi:[0,1]
	v_pk_mul_f32 v[6:7], v[6:7], v[10:11]
	v_cvt_pk_bf16_f32 v4, v4, v5
	v_fma_f32 v10, -v26, v30, 1.0
	v_fmac_f32_e32 v30, v10, v30
	v_div_scale_f32 v10, vcc, v37, v9, v37
	v_mul_f32_e32 v11, v10, v30
	v_fma_f32 v28, -v26, v11, v10
	v_fmac_f32_e32 v11, v28, v30
	v_fma_f32 v10, -v26, v11, v10
	v_div_scale_f32 v26, s[86:87], v8, v8, v36
	v_rcp_f32_e32 v28, v26
	v_div_fmas_f32 v10, v10, v30, v11
	v_div_fixup_f32 v9, v10, v9, v37
	v_mov_b32_e32 v32, v31
	v_fma_f32 v10, -v26, v28, 1.0
	v_fmac_f32_e32 v28, v10, v28
	v_div_scale_f32 v10, vcc, v36, v8, v36
	v_mul_f32_e32 v11, v10, v28
	v_fma_f32 v30, -v26, v11, v10
	v_fmac_f32_e32 v11, v30, v28
	v_fma_f32 v10, -v26, v11, v10
	v_div_fmas_f32 v26, v10, v28, v11
	v_mul_f32_e32 v10, 0xbfb8aa3b, v38
	v_mul_f32_e32 v11, 0xbfb8aa3b, v39
	v_exp_f32_e32 v10, v10
	v_exp_f32_e32 v11, v11
	v_div_fixup_f32 v8, v26, v8, v36
	v_pk_mul_f32 v[6:7], v[6:7], v[8:9]
	v_mov_b32_e32 v8, v22
	v_pk_add_f32 v[10:11], v[10:11], 1.0 op_sel_hi:[1,0]
	v_mov_b32_e32 v9, v24
	v_div_scale_f32 v22, s[86:87], v11, v11, v39
	v_rcp_f32_e32 v26, v22
	v_pk_mul_f32 v[8:9], v[50:51], v[8:9] op_sel_hi:[0,1]
	s_waitcnt vmcnt(0)
	v_mov_b32_e32 v12, v228
	v_mov_b32_e32 v13, v229
	v_mov_b32_e32 v14, v230
	v_mov_b32_e32 v15, v231
	v_pk_mul_f32 v[8:9], v[8:9], v[12:13]
	v_cvt_pk_bf16_f32 v5, v6, v7
	v_fma_f32 v12, -v22, v26, 1.0
	v_fmac_f32_e32 v26, v12, v26
	v_div_scale_f32 v12, vcc, v39, v11, v39
	v_mul_f32_e32 v13, v12, v26
	v_fma_f32 v24, -v22, v13, v12
	v_fmac_f32_e32 v13, v24, v26
	v_fma_f32 v12, -v22, v13, v12
	v_div_scale_f32 v22, s[86:87], v10, v10, v38
	v_rcp_f32_e32 v24, v22
	v_div_fmas_f32 v12, v12, v26, v13
	v_div_fixup_f32 v11, v12, v11, v39
	v_fma_f32 v12, -v22, v24, 1.0
	v_fmac_f32_e32 v24, v12, v24
	v_div_scale_f32 v12, vcc, v38, v10, v38
	v_mul_f32_e32 v13, v12, v24
	v_fma_f32 v26, -v22, v13, v12
	v_fmac_f32_e32 v13, v26, v24
	v_fma_f32 v12, -v22, v13, v12
	v_div_fmas_f32 v22, v12, v24, v13
	v_mul_f32_e32 v12, 0xbfb8aa3b, v40
	v_mul_f32_e32 v13, 0xbfb8aa3b, v41
	v_exp_f32_e32 v12, v12
	v_exp_f32_e32 v13, v13
	v_div_fixup_f32 v10, v22, v10, v38
	v_pk_mul_f32 v[8:9], v[10:11], v[8:9]
	v_mov_b32_e32 v10, v18
	v_pk_add_f32 v[12:13], v[12:13], 1.0 op_sel_hi:[1,0]
	v_mov_b32_e32 v11, v20
	v_div_scale_f32 v18, s[86:87], v13, v13, v41
	v_rcp_f32_e32 v22, v18
	v_pk_mul_f32 v[10:11], v[50:51], v[10:11] op_sel_hi:[0,1]
	v_pk_mul_f32 v[10:11], v[10:11], v[14:15]
	v_cvt_pk_bf16_f32 v6, v8, v9
	v_fma_f32 v14, -v18, v22, 1.0
	v_fmac_f32_e32 v22, v14, v22
	v_div_scale_f32 v14, vcc, v41, v13, v41
	v_mul_f32_e32 v15, v14, v22
	v_fma_f32 v20, -v18, v15, v14
	v_fmac_f32_e32 v15, v20, v22
	v_fma_f32 v14, -v18, v15, v14
	v_div_scale_f32 v18, s[86:87], v12, v12, v40
	v_rcp_f32_e32 v20, v18
	v_div_fmas_f32 v14, v14, v22, v15
	v_div_fixup_f32 v13, v14, v13, v41
	v_and_b32_e32 v26, 0xffff0000, v3
	v_fma_f32 v14, -v18, v20, 1.0
	v_fmac_f32_e32 v20, v14, v20
	v_div_scale_f32 v14, vcc, v40, v12, v40
	v_mul_f32_e32 v15, v14, v20
	v_fma_f32 v22, -v18, v15, v14
	v_fmac_f32_e32 v15, v22, v20
	v_fma_f32 v14, -v18, v15, v14
	v_div_fmas_f32 v14, v14, v20, v15
	v_div_fixup_f32 v12, v14, v12, v40
	v_pk_mul_f32 v[10:11], v[12:13], v[10:11]
	v_lshlrev_b32_e32 v12, 16, v0
	v_cvt_pk_bf16_f32 v7, v10, v11
	global_store_dwordx4 v[16:17], v[4:7], off offset:96
	s_nop 0
	v_and_b32_e32 v13, 0xffff0000, v0
	v_lshlrev_b32_e32 v14, 16, v1
	v_and_b32_e32 v15, 0xffff0000, v1
	v_mul_f32_e32 v0, 0xbfb8aa3b, v12
	v_mul_f32_e32 v1, 0xbfb8aa3b, v13
	v_exp_f32_e32 v0, v0
	v_exp_f32_e32 v1, v1
	v_lshlrev_b32_e32 v18, 16, v2
	v_and_b32_e32 v20, 0xffff0000, v2
	v_lshlrev_b32_e32 v22, 16, v3
	v_pk_add_f32 v[0:1], v[0:1], 1.0 op_sel_hi:[1,0]
	v_pk_mul_f32 v[2:3], v[50:51], v[32:33] op_sel_hi:[0,1]
	v_div_scale_f32 v24, s[0:1], v1, v1, v13
	v_rcp_f32_e32 v28, v24
	s_waitcnt vmcnt(1)
	v_mov_b32_e32 v4, v232
	v_mov_b32_e32 v5, v233
	v_mov_b32_e32 v6, v234
	v_mov_b32_e32 v7, v235
	v_pk_mul_f32 v[2:3], v[2:3], v[4:5]
	v_fma_f32 v4, -v24, v28, 1.0
	v_fmac_f32_e32 v28, v4, v28
	v_div_scale_f32 v4, vcc, v13, v1, v13
	v_mul_f32_e32 v5, v4, v28
	v_fma_f32 v30, -v24, v5, v4
	v_fmac_f32_e32 v5, v30, v28
	v_fma_f32 v4, -v24, v5, v4
	v_div_scale_f32 v24, s[0:1], v0, v0, v12
	v_rcp_f32_e32 v30, v24
	v_div_fmas_f32 v4, v4, v28, v5
	v_div_fixup_f32 v1, v4, v1, v13
	v_mov_b32_e32 v28, v27
	v_fma_f32 v4, -v24, v30, 1.0
	v_fmac_f32_e32 v30, v4, v30
	v_div_scale_f32 v4, vcc, v12, v0, v12
	v_mul_f32_e32 v13, v4, v30
	v_fma_f32 v5, -v24, v13, v4
	v_fmac_f32_e32 v13, v5, v30
	v_fma_f32 v24, -v24, v13, v4
	v_mul_f32_e32 v4, 0xbfb8aa3b, v14
	v_mul_f32_e32 v5, 0xbfb8aa3b, v15
	v_exp_f32_e32 v4, v4
	v_exp_f32_e32 v5, v5
	v_div_fmas_f32 v13, v24, v30, v13
	v_div_fixup_f32 v0, v13, v0, v12
	v_pk_mul_f32 v[0:1], v[2:3], v[0:1]
	v_pk_add_f32 v[2:3], v[4:5], 1.0 op_sel_hi:[1,0]
	v_pk_mul_f32 v[4:5], v[50:51], v[28:29] op_sel_hi:[0,1]
	v_div_scale_f32 v12, s[0:1], v3, v3, v15
	v_rcp_f32_e32 v13, v12
	v_pk_mul_f32 v[4:5], v[4:5], v[6:7]
	v_cvt_pk_bf16_f32 v0, v0, v1
	v_fma_f32 v6, -v12, v13, 1.0
	v_fmac_f32_e32 v13, v6, v13
	v_div_scale_f32 v6, vcc, v15, v3, v15
	v_mul_f32_e32 v7, v6, v13
	v_fma_f32 v24, -v12, v7, v6
	v_fmac_f32_e32 v7, v24, v13
	v_fma_f32 v6, -v12, v7, v6
	v_div_scale_f32 v12, s[0:1], v2, v2, v14
	v_rcp_f32_e32 v24, v12
	v_div_fmas_f32 v6, v6, v13, v7
	v_div_fixup_f32 v3, v6, v3, v15
	v_fma_f32 v6, -v12, v24, 1.0
	v_fmac_f32_e32 v24, v6, v24
	v_div_scale_f32 v6, vcc, v14, v2, v14
	v_mul_f32_e32 v13, v6, v24
	v_fma_f32 v7, -v12, v13, v6
	v_fmac_f32_e32 v13, v7, v24
	v_fma_f32 v12, -v12, v13, v6
	v_mul_f32_e32 v6, 0xbfb8aa3b, v18
	v_mul_f32_e32 v7, 0xbfb8aa3b, v20
	v_exp_f32_e32 v6, v6
	v_exp_f32_e32 v7, v7
	v_div_fmas_f32 v12, v12, v24, v13
	v_div_fixup_f32 v2, v12, v2, v14
	v_pk_mul_f32 v[2:3], v[4:5], v[2:3]
	v_pk_add_f32 v[4:5], v[6:7], 1.0 op_sel_hi:[1,0]
	v_mov_b32_e32 v24, v23
	v_div_scale_f32 v12, s[0:1], v5, v5, v20
	v_rcp_f32_e32 v13, v12
	v_pk_mul_f32 v[6:7], v[50:51], v[24:25] op_sel_hi:[0,1]
	s_waitcnt vmcnt(0)
	v_mov_b32_e32 v8, v124
	v_mov_b32_e32 v9, v125
	v_mov_b32_e32 v10, v126
	v_mov_b32_e32 v11, v127
	v_pk_mul_f32 v[6:7], v[6:7], v[8:9]
	v_cvt_pk_bf16_f32 v1, v2, v3
	v_fma_f32 v8, -v12, v13, 1.0
	v_fmac_f32_e32 v13, v8, v13
	v_div_scale_f32 v8, vcc, v20, v5, v20
	v_mul_f32_e32 v9, v8, v13
	v_fma_f32 v14, -v12, v9, v8
	v_fmac_f32_e32 v9, v14, v13
	v_fma_f32 v8, -v12, v9, v8
	v_div_scale_f32 v12, s[0:1], v4, v4, v18
	v_rcp_f32_e32 v14, v12
	v_div_fmas_f32 v8, v8, v13, v9
	v_div_fixup_f32 v5, v8, v5, v20
	v_mov_b32_e32 v20, v19
	v_fma_f32 v8, -v12, v14, 1.0
	v_fmac_f32_e32 v14, v8, v14
	v_div_scale_f32 v8, vcc, v18, v4, v18
	v_mul_f32_e32 v13, v8, v14
	v_fma_f32 v9, -v12, v13, v8
	v_fmac_f32_e32 v13, v9, v14
	v_fma_f32 v12, -v12, v13, v8
	v_mul_f32_e32 v8, 0xbfb8aa3b, v22
	v_mul_f32_e32 v9, 0xbfb8aa3b, v26
	v_exp_f32_e32 v8, v8
	v_exp_f32_e32 v9, v9
	v_div_fmas_f32 v12, v12, v14, v13
	v_div_fixup_f32 v4, v12, v4, v18
	v_pk_mul_f32 v[4:5], v[4:5], v[6:7]
	v_pk_add_f32 v[6:7], v[8:9], 1.0 op_sel_hi:[1,0]
	v_pk_mul_f32 v[8:9], v[50:51], v[20:21] op_sel_hi:[0,1]
	v_div_scale_f32 v12, s[0:1], v7, v7, v26
	v_rcp_f32_e32 v13, v12
	v_pk_mul_f32 v[8:9], v[8:9], v[10:11]
	v_cvt_pk_bf16_f32 v2, v4, v5
	v_fma_f32 v10, -v12, v13, 1.0
	v_fmac_f32_e32 v13, v10, v13
	v_div_scale_f32 v10, vcc, v26, v7, v26
	v_mul_f32_e32 v11, v10, v13
	v_fma_f32 v14, -v12, v11, v10
	v_fmac_f32_e32 v11, v14, v13
	v_fma_f32 v10, -v12, v11, v10
	v_div_scale_f32 v12, s[0:1], v6, v6, v22
	v_rcp_f32_e32 v14, v12
	v_div_fmas_f32 v10, v10, v13, v11
	v_div_fixup_f32 v7, v10, v7, v26
	v_fma_f32 v10, -v12, v14, 1.0
	v_fmac_f32_e32 v14, v10, v14
	v_div_scale_f32 v10, vcc, v22, v6, v22
	v_mul_f32_e32 v11, v10, v14
	v_fma_f32 v13, -v12, v11, v10
	v_fmac_f32_e32 v11, v13, v14
	v_fma_f32 v10, -v12, v11, v10
	v_div_fmas_f32 v10, v10, v14, v11
	v_div_fixup_f32 v6, v10, v6, v22
	v_pk_mul_f32 v[6:7], v[6:7], v[8:9]
	s_nop 0
	v_cvt_pk_bf16_f32 v3, v6, v7
	global_store_dwordx4 v[16:17], v[0:3], off offset:112
	s_barrier
	s_cbranch_scc0 .LBB0_311
